# speedup vs baseline: 1.0032x; 1.0023x over previous
; __device__ __forceinline__ float gelu_f(float x) {
;   const float c2 = 2.f * 0.7978845608028654f * 1.4426950408889634f;
;   float p = __builtin_fmaf(x * x, 0.044715f * c2, c2);
;   float e = __builtin_amdgcn_exp2f(-x * p);
;   return x * __builtin_amdgcn_rcpf(1.f + e);
; }
; template <int MODE>
; __device__ __forceinline__ void gemm_tile(const int ph, const int which, const int pm, const int pn) {
;     ...
;   if (MODE == 3) {
;     unsigned char* Gs = smem;
;     float rsv[2][4];
;     float4 w0[2], w1[2], w2[2], bb[2];
; #pragma unroll
;     for (int n = 0; n < 2; ++n) {
;       const int j = ecol + wc * 32 + n * 16 + fq * 4;
;       w0[n] = *(const float4*)(cw + j);
;       w1[n] = *(const float4*)(cw + DFF + j);
;       w2[n] = *(const float4*)(cw + 2 * DFF + j);
;       bb[n] = *(const float4*)(cb + j);
;     }
; #pragma unroll
;     for (int ai = 0; ai < 2; ++ai)
; #pragma unroll
;       for (int m = 0; m < 4; ++m) {
;         const int lr = ai * HALF + wr * 64 + m * 16 + fr;
;         const int gr = browC + lr;
;         const float s = scale[gr];
;         rsv[ai][m] = s;
; #pragma unroll
;         for (int n = 0; n < 2; ++n) {
;           const int c = wc * 32 + n * 16 + fq * 4;
;           f32x4 v = acc[ai][0][m][n];
;           uint2 o;
;           o.x = pack2(v[0] * s, v[1] * s);
;           o.y = pack2(v[2] * s, v[3] * s);
;           *(uint2*)(Gs + lr * 264 + c * 2) = o;
;         }
;       }
;     __syncthreads();
.LBB0_403:
	v_mov_b32_e32 v246, 0x3dd2d3e7
	v_mov_b32_e32 v247, 0x3dd2d3e7
	v_mov_b32_e32 v248, v209
	v_mov_b32_e32 v249, v209
	v_mov_b32_e32 v250, 1.0
	v_mov_b32_e32 v251, 1.0
	v_add_u32_e32 v164, s26, v163
	v_ashrrev_i32_e32 v165, 31, v164
	v_lshlrev_b32_e32 v28, 2, v162
	v_lshl_add_u64 v[26:27], v[164:165], 2, s[18:19]
	s_add_u32 s4, s2, 0x2c00
	s_movk_i32 s5, 0x108
	v_lshl_or_b32 v165, v0, 5, v28
	global_load_dword v194, v[26:27], off
	global_load_dword v184, v[26:27], off offset:64
	global_load_dword v174, v[26:27], off offset:128
	global_load_dword v172, v[26:27], off offset:192
	global_load_dword v170, v[26:27], off offset:512
	v_lshlrev_b32_e32 v29, 3, v162
	v_mul_lo_u32 v185, v163, s5
	s_addc_u32 s5, s3, 0
	v_or_b32_e32 v28, s6, v165
	v_lshl_or_b32 v0, v0, 6, v29
	global_load_dword v168, v[26:27], off offset:576
	global_load_dword v166, v[26:27], off offset:640
	global_load_dword v162, v[26:27], off offset:704
	s_add_u32 s16, s2, 0x5800
	v_ashrrev_i32_e32 v29, 31, v28
	v_or_b32_e32 v30, 16, v28
	s_addc_u32 s17, s3, 0
	v_lshlrev_b64 v[26:27], 2, v[28:29]
	v_ashrrev_i32_e32 v31, 31, v30
	v_lshl_add_u64 v[28:29], s[2:3], 0, v[26:27]
	v_lshl_add_u64 v[32:33], s[4:5], 0, v[26:27]
	v_lshl_add_u64 v[34:35], s[16:17], 0, v[26:27]
	v_lshl_add_u64 v[36:37], s[8:9], 0, v[26:27]
	v_lshlrev_b64 v[26:27], 2, v[30:31]
	v_lshl_add_u64 v[38:39], s[4:5], 0, v[26:27]
	v_lshl_add_u64 v[176:177], s[16:17], 0, v[26:27]
	global_load_dwordx4 v[42:45], v[32:33], off
	global_load_dwordx4 v[46:49], v[34:35], off
	global_load_dwordx4 v[50:53], v[28:29], off
	s_nop 0
	global_load_dwordx4 v[26:29], v[28:29], off offset:64
	s_nop 0
	global_load_dwordx4 v[54:57], v[36:37], off
	global_load_dwordx4 v[30:33], v[36:37], off offset:64
	s_nop 0
	global_load_dwordx4 v[38:41], v[38:39], off
	s_nop 0
	global_load_dwordx4 v[34:37], v[176:177], off
	v_add_u32_e32 v175, 0x1080, v185
	v_add_u32_e32 v173, 0x2100, v185
	v_add_u32_e32 v195, v0, v185
	v_add_u32_e32 v171, 0x3180, v185
	v_add_u32_e32 v169, 0x8400, v185
	v_add_u32_e32 v210, v0, v175
	v_add_u32_e32 v211, v0, v173
	v_add_u32_e32 v212, v0, v171
	v_add_u32_e32 v213, v0, v169
	v_cmp_gt_i32_e32 vcc, s36, v164
	s_ashr_i32 s7, s6, 31
	s_lshl_b64 s[2:3], s[6:7], 1
	s_add_u32 s2, s10, s2
	s_addc_u32 s3, s11, s3
	s_waitcnt vmcnt(15)
	v_pk_mul_f32 v[206:207], v[106:107], v[194:195] op_sel_hi:[1,0]
	v_pk_mul_f32 v[204:205], v[108:109], v[194:195] op_sel_hi:[1,0]
	v_pk_mul_f32 v[202:203], v[110:111], v[194:195] op_sel_hi:[1,0]
	v_pk_mul_f32 v[200:201], v[112:113], v[194:195] op_sel_hi:[1,0]
	s_waitcnt vmcnt(13)
	v_pk_mul_f32 v[182:183], v[126:127], v[174:175] op_sel_hi:[1,0]
	v_pk_mul_f32 v[180:181], v[128:129], v[174:175] op_sel_hi:[1,0]
	s_waitcnt vmcnt(12)
	v_pk_mul_f32 v[178:179], v[130:131], v[172:173] op_sel_hi:[1,0]
	v_pk_mul_f32 v[176:177], v[132:133], v[172:173] op_sel_hi:[1,0]
	v_pk_mul_f32 v[134:135], v[134:135], v[172:173] op_sel_hi:[1,0]
	v_pk_mul_f32 v[132:133], v[136:137], v[172:173] op_sel_hi:[1,0]
	v_pk_mul_f32 v[198:199], v[114:115], v[184:185] op_sel_hi:[1,0]
	v_pk_mul_f32 v[196:197], v[116:117], v[184:185] op_sel_hi:[1,0]
	v_pk_mul_f32 v[192:193], v[118:119], v[184:185] op_sel_hi:[1,0]
	v_pk_mul_f32 v[190:191], v[120:121], v[184:185] op_sel_hi:[1,0]
	v_pk_mul_f32 v[188:189], v[122:123], v[174:175] op_sel_hi:[1,0]
	v_pk_mul_f32 v[186:187], v[124:125], v[174:175] op_sel_hi:[1,0]
	s_waitcnt vmcnt(11)
	v_pk_mul_f32 v[130:131], v[158:159], v[170:171] op_sel_hi:[1,0]
	v_cvt_pk_bf16_f32 v106, v206, v207
	v_cvt_pk_bf16_f32 v107, v204, v205
	v_cvt_pk_bf16_f32 v108, v202, v203
	v_cvt_pk_bf16_f32 v109, v200, v201
	v_cvt_pk_bf16_f32 v116, v182, v183
	v_cvt_pk_bf16_f32 v117, v180, v181
	v_cvt_pk_bf16_f32 v118, v178, v179
	v_cvt_pk_bf16_f32 v119, v176, v177
	v_cvt_pk_bf16_f32 v120, v134, v135
	v_cvt_pk_bf16_f32 v121, v132, v133
	v_pk_mul_f32 v[128:129], v[160:161], v[170:171] op_sel_hi:[1,0]
	v_pk_mul_f32 v[126:127], v[154:155], v[170:171] op_sel_hi:[1,0]
	v_pk_mul_f32 v[124:125], v[156:157], v[170:171] op_sel_hi:[1,0]
	v_cvt_pk_bf16_f32 v110, v198, v199
	v_cvt_pk_bf16_f32 v111, v196, v197
	v_cvt_pk_bf16_f32 v112, v192, v193
	v_cvt_pk_bf16_f32 v113, v190, v191
	v_cvt_pk_bf16_f32 v114, v188, v189
	v_cvt_pk_bf16_f32 v115, v186, v187
	ds_write2_b64 v195, v[106:107], v[108:109] offset1:4
	ds_write2_b64 v210, v[110:111], v[112:113] offset1:4
	ds_write2_b64 v211, v[114:115], v[116:117] offset1:4
	ds_write2_b64 v212, v[118:119], v[120:121] offset1:4
	v_cvt_pk_bf16_f32 v106, v130, v131
	v_cvt_pk_bf16_f32 v107, v128, v129
	v_cvt_pk_bf16_f32 v108, v126, v127
	v_cvt_pk_bf16_f32 v109, v124, v125
	v_add_u32_e32 v154, 0x9480, v185
	s_waitcnt vmcnt(10)
	v_pk_mul_f32 v[122:123], v[150:151], v[168:169] op_sel_hi:[1,0]
	v_pk_mul_f32 v[120:121], v[152:153], v[168:169] op_sel_hi:[1,0]
	v_pk_mul_f32 v[118:119], v[146:147], v[168:169] op_sel_hi:[1,0]
	v_pk_mul_f32 v[116:117], v[148:149], v[168:169] op_sel_hi:[1,0]
	ds_write2_b64 v213, v[106:107], v[108:109] offset1:4
	v_add_u32_e32 v110, v0, v154
	v_cvt_pk_bf16_f32 v106, v122, v123
	v_cvt_pk_bf16_f32 v107, v120, v121
	v_cvt_pk_bf16_f32 v108, v118, v119
	v_cvt_pk_bf16_f32 v109, v116, v117
	ds_write2_b64 v110, v[106:107], v[108:109] offset1:4
	v_add_u32_e32 v146, 0xa500, v185
	s_waitcnt vmcnt(9)
	v_pk_mul_f32 v[114:115], v[142:143], v[166:167] op_sel_hi:[1,0]
	v_pk_mul_f32 v[112:113], v[144:145], v[166:167] op_sel_hi:[1,0]
	v_pk_mul_f32 v[110:111], v[138:139], v[166:167] op_sel_hi:[1,0]
	v_pk_mul_f32 v[108:109], v[140:141], v[166:167] op_sel_hi:[1,0]
	v_add_u32_e32 v147, v0, v146
	v_cvt_pk_bf16_f32 v106, v114, v115
	v_cvt_pk_bf16_f32 v107, v112, v113
	v_cvt_pk_bf16_f32 v136, v110, v111
	v_cvt_pk_bf16_f32 v137, v108, v109
	ds_write2_b64 v147, v[106:107], v[136:137] offset1:4
	v_add_u32_e32 v138, 0xb580, v185
	s_waitcnt vmcnt(8)
	v_pk_mul_f32 v[106:107], v[102:103], v[162:163] op_sel_hi:[1,0]
	v_pk_mul_f32 v[104:105], v[104:105], v[162:163] op_sel_hi:[1,0]
	v_pk_mul_f32 v[102:103], v[98:99], v[162:163] op_sel_hi:[1,0]
	v_pk_mul_f32 v[98:99], v[100:101], v[162:163] op_sel_hi:[1,0]
	v_add_u32_e32 v0, v0, v138
	v_cvt_pk_bf16_f32 v136, v106, v107
	v_cvt_pk_bf16_f32 v137, v104, v105
	v_cvt_pk_bf16_f32 v140, v102, v103
	v_cvt_pk_bf16_f32 v141, v98, v99
	ds_write2_b64 v0, v[136:137], v[140:141] offset1:4
	v_cndmask_b32_e32 v0, v224, v225, vcc
	v_and_b32_e32 v100, v0, v164
	v_cmp_lt_i32_e32 vcc, 0, v163
	v_cmp_eq_u32_e64 s[6:7], 0, v100
	v_cmp_ne_u32_e64 s[4:5], 0, v100
	s_or_b64 s[6:7], vcc, s[6:7]
	s_waitcnt lgkmcnt(0)
	s_barrier
; __device__ __forceinline__ float lo2f(unsigned u) { return __uint_as_float(u << 16); }
; __device__ __forceinline__ float hi2f(unsigned u) { return __uint_as_float(u & 0xffff0000u); }
; __device__ __forceinline__ float gelu_f(float x) {
;   const float c2 = 2.f * 0.7978845608028654f * 1.4426950408889634f;
;   float p = __builtin_fmaf(x * x, 0.044715f * c2, c2);
;   float e = __builtin_amdgcn_exp2f(-x * p);
;   return x * __builtin_amdgcn_rcpf(1.f + e);
; template <int MODE>
; __device__ __forceinline__ void gemm_tile(const int ph, const int which, const int pm, const int pn) {
;     ...
;       for (int m = 0; m < 4; ++m) {
;         const int lr = ai * HALF + wr * 64 + m * 16 + fr;
;         const int gr = browC + lr;
;         const int L = gr < 32768 ? 2048 : 4096;
;         const int pos = gr & (L - 1);
;         if ((lr >= 1 || pos == 0) && (lr <= 254 || pos == L - 1)) {
;           const float s = rsv[ai][m];
;           bf16_t* arow = C + (size_t)gr * DFF;
;   #pragma unroll
;         for (int n = 0; n < 2; ++n) {
;             const int c = wc * 32 + n * 16 + fq * 4;
;             uint2 pu = make_uint2(0u, 0u), nu = make_uint2(0u, 0u);
;             if (pos != 0) pu = *(const uint2*)(Gs + (lr - 1) * 264 + c * 2);
;             if (pos != L - 1) nu = *(const uint2*)(Gs + (lr + 1) * 264 + c * 2);
;             f32x4 g = acc[ai][0][m][n], v = acc[ai][1][m][n];
;             float g0 = w0[n].x * lo2f(pu.x) + w1[n].x * (g[0] * s) + w2[n].x * lo2f(nu.x) + bb[n].x;
;             float g1 = w0[n].y * hi2f(pu.x) + w1[n].y * (g[1] * s) + w2[n].y * hi2f(nu.x) + bb[n].y;
;             float g2 = w0[n].z * lo2f(pu.y) + w1[n].z * (g[2] * s) + w2[n].z * lo2f(nu.y) + bb[n].z;
;             float g3 = w0[n].w * hi2f(pu.y) + w1[n].w * (g[3] * s) + w2[n].w * hi2f(nu.y) + bb[n].w;
;             uint2 o;
;             o.x = pack2(gelu_f(g0) * (v[0] * s), gelu_f(g1) * (v[1] * s));
;             o.y = pack2(gelu_f(g2) * (v[2] * s), gelu_f(g3) * (v[3] * s));
;             *(uint2*)(arow + ecol + c) = o;
	s_and_saveexec_b64 s[10:11], s[6:7]
	s_cbranch_execz .LBB0_414
	s_movk_i32 s6, 0xff
	v_cmp_gt_i32_e64 s[6:7], s6, v163
	v_cmp_eq_u32_e64 s[8:9], v100, v0
	v_cmp_ne_u32_e32 vcc, v100, v0
	s_or_b64 s[6:7], s[6:7], s[8:9]
	s_and_b64 exec, exec, s[6:7]
	s_cbranch_execz .LBB0_414
	v_add_u32_e32 v139, 0xfffffef8, v185
	v_mov_b32_e32 v100, 0
	v_mov_b32_e32 v136, 0
	v_mov_b32_e32 v137, 0
	s_and_saveexec_b64 s[6:7], s[4:5]
	v_lshl_add_u32 v0, v165, 1, v139
	ds_read_b64 v[136:137], v0
	s_or_b64 exec, exec, s[6:7]
	v_mov_b32_e32 v101, 0
	s_and_saveexec_b64 s[6:7], vcc
	v_lshl_add_u32 v0, v165, 1, v185
	ds_read_b64 v[100:101], v0 offset:264
	s_or_b64 exec, exec, s[6:7]
	s_waitcnt lgkmcnt(0)
	v_lshlrev_b32_e32 v142, 16, v136
	v_and_b32_e32 v143, 0xffff0000, v136
	s_waitcnt vmcnt(5)
	v_pk_mul_f32 v[142:143], v[50:51], v[142:143]
	v_lshlrev_b32_e32 v144, 16, v100
	v_pk_fma_f32 v[142:143], v[42:43], v[206:207], v[142:143]
	v_and_b32_e32 v145, 0xffff0000, v100
	v_pk_fma_f32 v[142:143], v[46:47], v[144:145], v[142:143]
	v_mov_b32_e32 v195, v194
	s_waitcnt vmcnt(3)
	v_pk_add_f32 v[142:143], v[54:55], v[142:143]
	v_pk_mul_f32 v[94:95], v[94:95], v[194:195]
	v_pk_mul_f32 v[144:145], v[142:143], v[142:143]
	v_lshlrev_b32_e32 v136, 16, v137
	v_and_b32_e32 v137, 0xffff0000, v137
	v_mov_b64_e32 v[140:141], s[2:3]
	s_movk_i32 s6, 0x1600
	v_pk_mul_f32 v[96:97], v[96:97], v[194:195]
	v_mad_i64_i32 v[140:141], s[6:7], v164, s6, v[140:141]
	v_pk_fma_f32 v[144:145], v[144:145], v[246:247], v[248:249]
	s_nop 0
	v_pk_mul_f32 v[144:145], v[144:145], v[142:143] neg_lo:[0,1] neg_hi:[0,1]
	s_nop 0
	v_exp_f32_e32 v144, v144
	v_exp_f32_e32 v145, v145
	s_nop 0
	v_pk_add_f32 v[144:145], v[144:145], v[250:251]
	s_nop 0
	v_rcp_f32_e32 v144, v144
	v_rcp_f32_e32 v145, v145
	s_nop 0
	s_nop 0
	v_pk_mul_f32 v[142:143], v[142:143], v[144:145]
	s_nop 0
	v_pk_mul_f32 v[94:95], v[94:95], v[142:143]
	s_nop 0
	v_cvt_pk_bf16_f32 v100, v94, v95
	v_pk_mul_f32 v[94:95], v[52:53], v[136:137]
	v_lshlrev_b32_e32 v136, 16, v101
	v_pk_fma_f32 v[94:95], v[44:45], v[204:205], v[94:95]
	v_and_b32_e32 v137, 0xffff0000, v101
	v_pk_fma_f32 v[94:95], v[48:49], v[136:137], v[94:95]
	s_nop 0
	v_pk_add_f32 v[94:95], v[56:57], v[94:95]
	s_nop 0
	v_pk_mul_f32 v[136:137], v[94:95], v[94:95]
	s_nop 0
	s_nop 0
	s_nop 0
	v_pk_fma_f32 v[136:137], v[136:137], v[246:247], v[248:249]
	s_nop 0
	v_pk_mul_f32 v[136:137], v[136:137], v[94:95] neg_lo:[0,1] neg_hi:[0,1]
	s_nop 0
	v_exp_f32_e32 v136, v136
	v_exp_f32_e32 v137, v137
	s_nop 0
	v_pk_add_f32 v[136:137], v[136:137], v[250:251]
	s_nop 0
	v_rcp_f32_e32 v136, v136
	v_rcp_f32_e32 v137, v137
	s_nop 0
	v_lshlrev_b32_e32 v0, 1, v165
	v_pk_mul_f32 v[94:95], v[94:95], v[136:137]
	s_nop 0
	v_pk_mul_f32 v[94:95], v[96:97], v[94:95]
	v_mov_b32_e32 v96, 0
	v_cvt_pk_bf16_f32 v101, v94, v95
	v_lshl_add_u64 v[94:95], v[140:141], 0, v[0:1]
	global_store_dwordx2 v[94:95], v[100:101], off
	v_or_b32_e32 v0, 16, v165
	v_mov_b32_e32 v100, 0
	v_mov_b32_e32 v101, 0
	s_and_saveexec_b64 s[6:7], s[4:5]
	v_lshl_add_u32 v97, v0, 1, v139
	ds_read_b64 v[100:101], v97
	s_or_b64 exec, exec, s[6:7]
	v_mov_b32_e32 v97, 0
	s_and_saveexec_b64 s[4:5], vcc
	v_lshl_add_u32 v0, v0, 1, v185
	ds_read_b64 v[96:97], v0 offset:264
	s_or_b64 exec, exec, s[4:5]
	s_waitcnt lgkmcnt(0)
	v_lshlrev_b32_e32 v136, 16, v100
	v_and_b32_e32 v137, 0xffff0000, v100
	v_pk_mul_f32 v[136:137], v[26:27], v[136:137]
	v_lshlrev_b32_e32 v140, 16, v96
	s_waitcnt vmcnt(2)
	v_pk_fma_f32 v[136:137], v[38:39], v[202:203], v[136:137]
	v_and_b32_e32 v141, 0xffff0000, v96
	s_waitcnt vmcnt(1)
	v_pk_fma_f32 v[136:137], v[34:35], v[140:141], v[136:137]
	v_lshlrev_b32_e32 v100, 16, v101
	v_pk_add_f32 v[136:137], v[30:31], v[136:137]
	v_and_b32_e32 v101, 0xffff0000, v101
	v_pk_mul_f32 v[140:141], v[136:137], v[136:137]
	v_pk_mul_f32 v[100:101], v[28:29], v[100:101]
	v_pk_fma_f32 v[100:101], v[40:41], v[200:201], v[100:101]
	v_lshlrev_b32_e32 v96, 16, v97
	v_and_b32_e32 v97, 0xffff0000, v97
	v_pk_fma_f32 v[96:97], v[36:37], v[96:97], v[100:101]
	v_pk_mul_f32 v[90:91], v[90:91], v[194:195]
	v_pk_add_f32 v[96:97], v[32:33], v[96:97]
	v_pk_mul_f32 v[100:101], v[96:97], v[96:97]
	v_pk_fma_f32 v[140:141], v[140:141], v[246:247], v[248:249]
	s_nop 0
	v_pk_mul_f32 v[140:141], v[140:141], v[136:137] neg_lo:[0,1] neg_hi:[0,1]
	s_nop 0
	v_exp_f32_e32 v140, v140
	v_exp_f32_e32 v141, v141
	s_nop 0
	v_pk_add_f32 v[140:141], v[140:141], v[250:251]
	s_nop 0
	v_rcp_f32_e32 v140, v140
	v_rcp_f32_e32 v141, v141
	s_nop 0
	v_pk_mul_f32 v[136:137], v[136:137], v[140:141]
	v_pk_mul_f32 v[92:93], v[92:93], v[194:195]
	v_pk_mul_f32 v[90:91], v[90:91], v[136:137]
	v_cvt_pk_bf16_f32 v90, v90, v91
	v_pk_fma_f32 v[100:101], v[100:101], v[246:247], v[248:249]
	s_nop 0
	v_pk_mul_f32 v[100:101], v[100:101], v[96:97] neg_lo:[0,1] neg_hi:[0,1]
	s_nop 0
	v_exp_f32_e32 v100, v100
	v_exp_f32_e32 v101, v101
	s_nop 0
	v_pk_add_f32 v[100:101], v[100:101], v[250:251]
	s_nop 0
	v_rcp_f32_e32 v100, v100
	v_rcp_f32_e32 v101, v101
	s_nop 0
	s_nop 0
	v_pk_mul_f32 v[96:97], v[96:97], v[100:101]
	s_nop 0
	v_pk_mul_f32 v[92:93], v[92:93], v[96:97]
	s_nop 0
	v_cvt_pk_bf16_f32 v91, v92, v93
	global_store_dwordx2 v[94:95], v[90:91], off offset:32
; __device__ __forceinline__ float lo2f(unsigned u) { return __uint_as_float(u << 16); }
; __device__ __forceinline__ float hi2f(unsigned u) { return __uint_as_float(u & 0xffff0000u); }
; __device__ __forceinline__ float gelu_f(float x) {
;   const float c2 = 2.f * 0.7978845608028654f * 1.4426950408889634f;
;   float p = __builtin_fmaf(x * x, 0.044715f * c2, c2);
;   float e = __builtin_amdgcn_exp2f(-x * p);
;   return x * __builtin_amdgcn_rcpf(1.f + e);
; template <int MODE>
; __device__ __forceinline__ void gemm_tile(const int ph, const int which, const int pm, const int pn) {
;     ...
;       for (int m = 0; m < 4; ++m) {
;         const int lr = ai * HALF + wr * 64 + m * 16 + fr;
;         const int gr = browC + lr;
;         const int L = gr < 32768 ? 2048 : 4096;
;         const int pos = gr & (L - 1);
;         if ((lr >= 1 || pos == 0) && (lr <= 254 || pos == L - 1)) {
;           const float s = rsv[ai][m];
;           bf16_t* arow = C + (size_t)gr * DFF;
;   #pragma unroll
;         for (int n = 0; n < 2; ++n) {
;             const int c = wc * 32 + n * 16 + fq * 4;
;             uint2 pu = make_uint2(0u, 0u), nu = make_uint2(0u, 0u);
;             if (pos != 0) pu = *(const uint2*)(Gs + (lr - 1) * 264 + c * 2);
;             if (pos != L - 1) nu = *(const uint2*)(Gs + (lr + 1) * 264 + c * 2);
;             f32x4 g = acc[ai][0][m][n], v = acc[ai][1][m][n];
;             float g0 = w0[n].x * lo2f(pu.x) + w1[n].x * (g[0] * s) + w2[n].x * lo2f(nu.x) + bb[n].x;
;             float g1 = w0[n].y * hi2f(pu.x) + w1[n].y * (g[1] * s) + w2[n].y * hi2f(nu.x) + bb[n].y;
;             float g2 = w0[n].z * lo2f(pu.y) + w1[n].z * (g[2] * s) + w2[n].z * lo2f(nu.y) + bb[n].z;
;             float g3 = w0[n].w * hi2f(pu.y) + w1[n].w * (g[3] * s) + w2[n].w * hi2f(nu.y) + bb[n].w;
;             uint2 o;
;             o.x = pack2(gelu_f(g0) * (v[0] * s), gelu_f(g1) * (v[1] * s));
;             o.y = pack2(gelu_f(g2) * (v[2] * s), gelu_f(g3) * (v[3] * s));
;             *(uint2*)(arow + ecol + c) = o;
.LBB0_414:
	s_or_b64 exec, exec, s[10:11]
	v_or_b32_e32 v90, 16, v163
	v_add_u32_e32 v0, s26, v90
	v_cmp_gt_i32_e32 vcc, s36, v0
	s_nop 1
	v_cndmask_b32_e32 v91, v224, v225, vcc
	v_and_b32_e32 v92, v91, v0
	v_cmp_lt_i32_e32 vcc, -1, v167
	v_cmp_eq_u32_e64 s[4:5], 0, v92
	v_cmp_ne_u32_e64 s[6:7], 0, v92
	s_or_b64 s[4:5], vcc, s[4:5]
	s_and_saveexec_b64 s[16:17], s[4:5]
	s_cbranch_execz .LBB0_425
	s_movk_i32 s4, 0xff
	v_cmp_gt_i32_e64 s[8:9], s4, v90
	v_cmp_eq_u32_e64 s[10:11], v92, v91
	v_cmp_ne_u32_e64 s[4:5], v92, v91
	s_or_b64 s[8:9], s[8:9], s[10:11]
	s_and_b64 exec, exec, s[8:9]
	s_cbranch_execz .LBB0_425
	v_add_u32_e32 v94, 0xfffffef8, v175
	v_mov_b32_e32 v90, 0
	v_mov_b32_e32 v92, 0
	v_mov_b32_e32 v93, 0
	s_and_saveexec_b64 s[8:9], s[6:7]
	v_lshl_add_u32 v91, v165, 1, v94
	ds_read_b64 v[92:93], v91
	s_or_b64 exec, exec, s[8:9]
	v_mov_b32_e32 v91, 0
	s_and_saveexec_b64 s[8:9], s[4:5]
	v_lshl_add_u32 v90, v165, 1, v175
	ds_read_b64 v[90:91], v90 offset:264
	s_or_b64 exec, exec, s[8:9]
	s_waitcnt lgkmcnt(0)
	v_lshlrev_b32_e32 v100, 16, v92
	v_and_b32_e32 v101, 0xffff0000, v92
	s_waitcnt vmcnt(5)
	v_pk_mul_f32 v[100:101], v[50:51], v[100:101]
	v_lshlrev_b32_e32 v136, 16, v90
	v_pk_fma_f32 v[100:101], v[42:43], v[198:199], v[100:101]
	v_and_b32_e32 v137, 0xffff0000, v90
	v_pk_fma_f32 v[100:101], v[46:47], v[136:137], v[100:101]
	v_mov_b64_e32 v[96:97], s[2:3]
	s_waitcnt vmcnt(3)
	v_pk_add_f32 v[100:101], v[54:55], v[100:101]
	s_movk_i32 s8, 0x1600
	v_pk_mul_f32 v[136:137], v[100:101], v[100:101]
	v_mad_i64_i32 v[96:97], s[8:9], v0, s8, v[96:97]
	v_mov_b32_e32 v185, v184
	v_pk_mul_f32 v[86:87], v[86:87], v[184:185]
	v_lshlrev_b32_e32 v92, 16, v93
	v_and_b32_e32 v93, 0xffff0000, v93
	v_pk_mul_f32 v[88:89], v[88:89], v[184:185]
	v_pk_fma_f32 v[136:137], v[136:137], v[246:247], v[248:249]
	s_nop 0
	v_pk_mul_f32 v[136:137], v[136:137], v[100:101] neg_lo:[0,1] neg_hi:[0,1]
	s_nop 0
	v_exp_f32_e32 v136, v136
	v_exp_f32_e32 v137, v137
	s_nop 0
	v_pk_add_f32 v[136:137], v[136:137], v[250:251]
	s_nop 0
	v_rcp_f32_e32 v136, v136
	v_rcp_f32_e32 v137, v137
	s_nop 0
	s_nop 0
	v_pk_mul_f32 v[100:101], v[100:101], v[136:137]
	s_nop 0
	v_pk_mul_f32 v[86:87], v[86:87], v[100:101]
	s_nop 0
	v_cvt_pk_bf16_f32 v90, v86, v87
	v_pk_mul_f32 v[86:87], v[52:53], v[92:93]
	v_lshlrev_b32_e32 v92, 16, v91
	v_pk_fma_f32 v[86:87], v[44:45], v[196:197], v[86:87]
	v_and_b32_e32 v93, 0xffff0000, v91
	v_pk_fma_f32 v[86:87], v[48:49], v[92:93], v[86:87]
	s_nop 0
	v_pk_add_f32 v[86:87], v[56:57], v[86:87]
	s_nop 0
	v_pk_mul_f32 v[92:93], v[86:87], v[86:87]
	s_nop 0
	s_nop 0
	s_nop 0
	v_pk_fma_f32 v[92:93], v[92:93], v[246:247], v[248:249]
	s_nop 0
	v_pk_mul_f32 v[92:93], v[92:93], v[86:87] neg_lo:[0,1] neg_hi:[0,1]
	s_nop 0
	v_exp_f32_e32 v92, v92
	v_exp_f32_e32 v93, v93
	s_nop 0
	v_pk_add_f32 v[92:93], v[92:93], v[250:251]
	s_nop 0
	v_rcp_f32_e32 v92, v92
	v_rcp_f32_e32 v93, v93
	s_nop 0
	v_lshlrev_b32_e32 v0, 1, v165
	v_pk_mul_f32 v[86:87], v[86:87], v[92:93]
	s_nop 0
	v_pk_mul_f32 v[86:87], v[88:89], v[86:87]
	v_mov_b32_e32 v88, 0
	v_cvt_pk_bf16_f32 v91, v86, v87
	v_lshl_add_u64 v[86:87], v[96:97], 0, v[0:1]
	global_store_dwordx2 v[86:87], v[90:91], off
	v_or_b32_e32 v0, 16, v165
	v_mov_b32_e32 v90, 0
	v_mov_b32_e32 v91, 0
	s_and_saveexec_b64 s[8:9], s[6:7]
	v_lshl_add_u32 v89, v0, 1, v94
	ds_read_b64 v[90:91], v89
	s_or_b64 exec, exec, s[8:9]
	v_mov_b32_e32 v89, 0
	s_and_saveexec_b64 s[6:7], s[4:5]
	v_lshl_add_u32 v0, v0, 1, v175
	ds_read_b64 v[88:89], v0 offset:264
	s_or_b64 exec, exec, s[6:7]
	s_waitcnt lgkmcnt(0)
	v_lshlrev_b32_e32 v92, 16, v90
	v_and_b32_e32 v93, 0xffff0000, v90
	v_pk_mul_f32 v[92:93], v[26:27], v[92:93]
	v_lshlrev_b32_e32 v94, 16, v88
	s_waitcnt vmcnt(2)
	v_pk_fma_f32 v[92:93], v[38:39], v[192:193], v[92:93]
	v_and_b32_e32 v95, 0xffff0000, v88
	s_waitcnt vmcnt(1)
	v_pk_fma_f32 v[92:93], v[34:35], v[94:95], v[92:93]
	v_lshlrev_b32_e32 v90, 16, v91
	v_pk_add_f32 v[92:93], v[30:31], v[92:93]
	v_and_b32_e32 v91, 0xffff0000, v91
	v_pk_mul_f32 v[94:95], v[92:93], v[92:93]
	v_pk_mul_f32 v[90:91], v[28:29], v[90:91]
	v_pk_fma_f32 v[90:91], v[40:41], v[190:191], v[90:91]
	v_lshlrev_b32_e32 v88, 16, v89
	v_and_b32_e32 v89, 0xffff0000, v89
	v_pk_fma_f32 v[88:89], v[36:37], v[88:89], v[90:91]
	v_pk_mul_f32 v[82:83], v[82:83], v[184:185]
	v_pk_add_f32 v[88:89], v[32:33], v[88:89]
	v_pk_mul_f32 v[90:91], v[88:89], v[88:89]
	v_pk_fma_f32 v[94:95], v[94:95], v[246:247], v[248:249]
	s_nop 0
	v_pk_mul_f32 v[94:95], v[94:95], v[92:93] neg_lo:[0,1] neg_hi:[0,1]
	s_nop 0
	v_exp_f32_e32 v94, v94
	v_exp_f32_e32 v95, v95
	s_nop 0
	v_pk_add_f32 v[94:95], v[94:95], v[250:251]
	s_nop 0
	v_rcp_f32_e32 v94, v94
	v_rcp_f32_e32 v95, v95
	s_nop 0
	v_pk_mul_f32 v[92:93], v[92:93], v[94:95]
	v_pk_mul_f32 v[84:85], v[84:85], v[184:185]
	v_pk_mul_f32 v[82:83], v[82:83], v[92:93]
	v_cvt_pk_bf16_f32 v82, v82, v83
	v_pk_fma_f32 v[90:91], v[90:91], v[246:247], v[248:249]
	s_nop 0
	v_pk_mul_f32 v[90:91], v[90:91], v[88:89] neg_lo:[0,1] neg_hi:[0,1]
	s_nop 0
	v_exp_f32_e32 v90, v90
	v_exp_f32_e32 v91, v91
	s_nop 0
	v_pk_add_f32 v[90:91], v[90:91], v[250:251]
	s_nop 0
	v_rcp_f32_e32 v90, v90
	v_rcp_f32_e32 v91, v91
	s_nop 0
	s_nop 0
	v_pk_mul_f32 v[88:89], v[88:89], v[90:91]
	s_nop 0
	v_pk_mul_f32 v[84:85], v[84:85], v[88:89]
	s_nop 0
	v_cvt_pk_bf16_f32 v83, v84, v85
	global_store_dwordx2 v[86:87], v[82:83], off offset:32
; __device__ __forceinline__ float lo2f(unsigned u) { return __uint_as_float(u << 16); }
; __device__ __forceinline__ float hi2f(unsigned u) { return __uint_as_float(u & 0xffff0000u); }
; __device__ __forceinline__ float gelu_f(float x) {
;   const float c2 = 2.f * 0.7978845608028654f * 1.4426950408889634f;
;   float p = __builtin_fmaf(x * x, 0.044715f * c2, c2);
;   float e = __builtin_amdgcn_exp2f(-x * p);
;   return x * __builtin_amdgcn_rcpf(1.f + e);
; template <int MODE>
; __device__ __forceinline__ void gemm_tile(const int ph, const int which, const int pm, const int pn) {
;     ...
;       for (int m = 0; m < 4; ++m) {
;         const int lr = ai * HALF + wr * 64 + m * 16 + fr;
;         const int gr = browC + lr;
;         const int L = gr < 32768 ? 2048 : 4096;
;         const int pos = gr & (L - 1);
;         if ((lr >= 1 || pos == 0) && (lr <= 254 || pos == L - 1)) {
;           const float s = rsv[ai][m];
;           bf16_t* arow = C + (size_t)gr * DFF;
;   #pragma unroll
;         for (int n = 0; n < 2; ++n) {
;             const int c = wc * 32 + n * 16 + fq * 4;
;             uint2 pu = make_uint2(0u, 0u), nu = make_uint2(0u, 0u);
;             if (pos != 0) pu = *(const uint2*)(Gs + (lr - 1) * 264 + c * 2);
;             if (pos != L - 1) nu = *(const uint2*)(Gs + (lr + 1) * 264 + c * 2);
;             f32x4 g = acc[ai][0][m][n], v = acc[ai][1][m][n];
;             float g0 = w0[n].x * lo2f(pu.x) + w1[n].x * (g[0] * s) + w2[n].x * lo2f(nu.x) + bb[n].x;
;             float g1 = w0[n].y * hi2f(pu.x) + w1[n].y * (g[1] * s) + w2[n].y * hi2f(nu.x) + bb[n].y;
;             float g2 = w0[n].z * lo2f(pu.y) + w1[n].z * (g[2] * s) + w2[n].z * lo2f(nu.y) + bb[n].z;
;             float g3 = w0[n].w * hi2f(pu.y) + w1[n].w * (g[3] * s) + w2[n].w * hi2f(nu.y) + bb[n].w;
;             uint2 o;
;             o.x = pack2(gelu_f(g0) * (v[0] * s), gelu_f(g1) * (v[1] * s));
;             o.y = pack2(gelu_f(g2) * (v[2] * s), gelu_f(g3) * (v[3] * s));
;             *(uint2*)(arow + ecol + c) = o;
.LBB0_425:
	s_or_b64 exec, exec, s[16:17]
	v_or_b32_e32 v82, 32, v163
	v_add_u32_e32 v0, s26, v82
	v_cmp_gt_i32_e64 s[4:5], s36, v0
	s_nop 1
	v_cndmask_b32_e64 v83, v224, v225, s[4:5]
	v_and_b32_e32 v84, v83, v0
	v_cmp_eq_u32_e64 s[4:5], 0, v84
	v_cmp_ne_u32_e64 s[6:7], 0, v84
	s_or_b64 s[4:5], vcc, s[4:5]
	s_and_saveexec_b64 s[16:17], s[4:5]
	s_cbranch_execz .LBB0_436
	s_movk_i32 s4, 0xff
	v_cmp_gt_i32_e64 s[8:9], s4, v82
	v_cmp_eq_u32_e64 s[10:11], v84, v83
	v_cmp_ne_u32_e64 s[4:5], v84, v83
	s_or_b64 s[8:9], s[8:9], s[10:11]
	s_and_b64 exec, exec, s[8:9]
	s_cbranch_execz .LBB0_436
	v_add_u32_e32 v86, 0xfffffef8, v173
	v_mov_b32_e32 v82, 0
	v_mov_b32_e32 v84, 0
	v_mov_b32_e32 v85, 0
	s_and_saveexec_b64 s[8:9], s[6:7]
	v_lshl_add_u32 v83, v165, 1, v86
	ds_read_b64 v[84:85], v83
	s_or_b64 exec, exec, s[8:9]
	v_mov_b32_e32 v83, 0
	s_and_saveexec_b64 s[8:9], s[4:5]
	v_lshl_add_u32 v82, v165, 1, v173
	ds_read_b64 v[82:83], v82 offset:264
	s_or_b64 exec, exec, s[8:9]
	s_waitcnt lgkmcnt(0)
	v_lshlrev_b32_e32 v90, 16, v84
	v_and_b32_e32 v91, 0xffff0000, v84
	s_waitcnt vmcnt(5)
	v_pk_mul_f32 v[90:91], v[50:51], v[90:91]
	v_lshlrev_b32_e32 v92, 16, v82
	v_pk_fma_f32 v[90:91], v[42:43], v[188:189], v[90:91]
	v_and_b32_e32 v93, 0xffff0000, v82
	v_pk_fma_f32 v[90:91], v[46:47], v[92:93], v[90:91]
	v_mov_b64_e32 v[88:89], s[2:3]
	s_waitcnt vmcnt(3)
	v_pk_add_f32 v[90:91], v[54:55], v[90:91]
	s_movk_i32 s8, 0x1600
	v_pk_mul_f32 v[92:93], v[90:91], v[90:91]
	v_mad_i64_i32 v[88:89], s[8:9], v0, s8, v[88:89]
	v_mov_b32_e32 v175, v174
	v_pk_mul_f32 v[78:79], v[78:79], v[174:175]
	v_lshlrev_b32_e32 v84, 16, v85
	v_and_b32_e32 v85, 0xffff0000, v85
	v_pk_mul_f32 v[80:81], v[80:81], v[174:175]
	v_pk_fma_f32 v[92:93], v[92:93], v[246:247], v[248:249]
	s_nop 0
	v_pk_mul_f32 v[92:93], v[92:93], v[90:91] neg_lo:[0,1] neg_hi:[0,1]
	s_nop 0
	v_exp_f32_e32 v92, v92
	v_exp_f32_e32 v93, v93
	s_nop 0
	v_pk_add_f32 v[92:93], v[92:93], v[250:251]
	s_nop 0
	v_rcp_f32_e32 v92, v92
	v_rcp_f32_e32 v93, v93
	s_nop 0
	s_nop 0
	v_pk_mul_f32 v[90:91], v[90:91], v[92:93]
	s_nop 0
	v_pk_mul_f32 v[78:79], v[78:79], v[90:91]
	s_nop 0
	v_cvt_pk_bf16_f32 v82, v78, v79
	v_pk_mul_f32 v[78:79], v[52:53], v[84:85]
	v_lshlrev_b32_e32 v84, 16, v83
	v_pk_fma_f32 v[78:79], v[44:45], v[186:187], v[78:79]
	v_and_b32_e32 v85, 0xffff0000, v83
	v_pk_fma_f32 v[78:79], v[48:49], v[84:85], v[78:79]
	s_nop 0
	v_pk_add_f32 v[78:79], v[56:57], v[78:79]
	s_nop 0
	v_pk_mul_f32 v[84:85], v[78:79], v[78:79]
	s_nop 0
	s_nop 0
	s_nop 0
	v_pk_fma_f32 v[84:85], v[84:85], v[246:247], v[248:249]
	s_nop 0
	v_pk_mul_f32 v[84:85], v[84:85], v[78:79] neg_lo:[0,1] neg_hi:[0,1]
	s_nop 0
	v_exp_f32_e32 v84, v84
	v_exp_f32_e32 v85, v85
	s_nop 0
	v_pk_add_f32 v[84:85], v[84:85], v[250:251]
	s_nop 0
	v_rcp_f32_e32 v84, v84
	v_rcp_f32_e32 v85, v85
	s_nop 0
	v_lshlrev_b32_e32 v0, 1, v165
	v_pk_mul_f32 v[78:79], v[78:79], v[84:85]
	s_nop 0
	v_pk_mul_f32 v[78:79], v[80:81], v[78:79]
	v_mov_b32_e32 v80, 0
	v_cvt_pk_bf16_f32 v83, v78, v79
	v_lshl_add_u64 v[78:79], v[88:89], 0, v[0:1]
	global_store_dwordx2 v[78:79], v[82:83], off
	v_or_b32_e32 v0, 16, v165
	v_mov_b32_e32 v82, 0
	v_mov_b32_e32 v83, 0
	s_and_saveexec_b64 s[8:9], s[6:7]
	v_lshl_add_u32 v81, v0, 1, v86
	ds_read_b64 v[82:83], v81
	s_or_b64 exec, exec, s[8:9]
	v_mov_b32_e32 v81, 0
	s_and_saveexec_b64 s[6:7], s[4:5]
	v_lshl_add_u32 v0, v0, 1, v173
	ds_read_b64 v[80:81], v0 offset:264
	s_or_b64 exec, exec, s[6:7]
	s_waitcnt lgkmcnt(0)
	v_lshlrev_b32_e32 v84, 16, v82
	v_and_b32_e32 v85, 0xffff0000, v82
	v_pk_mul_f32 v[84:85], v[26:27], v[84:85]
	v_lshlrev_b32_e32 v86, 16, v80
	s_waitcnt vmcnt(2)
	v_pk_fma_f32 v[84:85], v[38:39], v[182:183], v[84:85]
	v_and_b32_e32 v87, 0xffff0000, v80
	s_waitcnt vmcnt(1)
	v_pk_fma_f32 v[84:85], v[34:35], v[86:87], v[84:85]
	v_lshlrev_b32_e32 v82, 16, v83
	v_pk_add_f32 v[84:85], v[30:31], v[84:85]
	v_and_b32_e32 v83, 0xffff0000, v83
	v_pk_mul_f32 v[86:87], v[84:85], v[84:85]
	v_pk_mul_f32 v[82:83], v[28:29], v[82:83]
	v_pk_fma_f32 v[82:83], v[40:41], v[180:181], v[82:83]
	v_lshlrev_b32_e32 v80, 16, v81
	v_and_b32_e32 v81, 0xffff0000, v81
	v_pk_fma_f32 v[80:81], v[36:37], v[80:81], v[82:83]
	v_pk_mul_f32 v[74:75], v[74:75], v[174:175]
	v_pk_add_f32 v[80:81], v[32:33], v[80:81]
	v_pk_mul_f32 v[82:83], v[80:81], v[80:81]
	v_pk_fma_f32 v[86:87], v[86:87], v[246:247], v[248:249]
	s_nop 0
	v_pk_mul_f32 v[86:87], v[86:87], v[84:85] neg_lo:[0,1] neg_hi:[0,1]
	s_nop 0
	v_exp_f32_e32 v86, v86
	v_exp_f32_e32 v87, v87
	s_nop 0
	v_pk_add_f32 v[86:87], v[86:87], v[250:251]
	s_nop 0
	v_rcp_f32_e32 v86, v86
	v_rcp_f32_e32 v87, v87
	s_nop 0
	v_pk_mul_f32 v[84:85], v[84:85], v[86:87]
	v_pk_mul_f32 v[76:77], v[76:77], v[174:175]
	v_pk_mul_f32 v[74:75], v[74:75], v[84:85]
	v_cvt_pk_bf16_f32 v74, v74, v75
	v_pk_fma_f32 v[82:83], v[82:83], v[246:247], v[248:249]
	s_nop 0
	v_pk_mul_f32 v[82:83], v[82:83], v[80:81] neg_lo:[0,1] neg_hi:[0,1]
	s_nop 0
	v_exp_f32_e32 v82, v82
	v_exp_f32_e32 v83, v83
	s_nop 0
	v_pk_add_f32 v[82:83], v[82:83], v[250:251]
	s_nop 0
	v_rcp_f32_e32 v82, v82
	v_rcp_f32_e32 v83, v83
	s_nop 0
	s_nop 0
	v_pk_mul_f32 v[80:81], v[80:81], v[82:83]
	s_nop 0
	v_pk_mul_f32 v[76:77], v[76:77], v[80:81]
	s_nop 0
	v_cvt_pk_bf16_f32 v75, v76, v77
	global_store_dwordx2 v[78:79], v[74:75], off offset:32
; __device__ __forceinline__ float lo2f(unsigned u) { return __uint_as_float(u << 16); }
; __device__ __forceinline__ float hi2f(unsigned u) { return __uint_as_float(u & 0xffff0000u); }
; __device__ __forceinline__ float gelu_f(float x) {
;   const float c2 = 2.f * 0.7978845608028654f * 1.4426950408889634f;
;   float p = __builtin_fmaf(x * x, 0.044715f * c2, c2);
;   float e = __builtin_amdgcn_exp2f(-x * p);
;   return x * __builtin_amdgcn_rcpf(1.f + e);
; template <int MODE>
; __device__ __forceinline__ void gemm_tile(const int ph, const int which, const int pm, const int pn) {
;     ...
;       for (int m = 0; m < 4; ++m) {
;         const int lr = ai * HALF + wr * 64 + m * 16 + fr;
;         const int gr = browC + lr;
;         const int L = gr < 32768 ? 2048 : 4096;
;         const int pos = gr & (L - 1);
;         if ((lr >= 1 || pos == 0) && (lr <= 254 || pos == L - 1)) {
;           const float s = rsv[ai][m];
;           bf16_t* arow = C + (size_t)gr * DFF;
;   #pragma unroll
;         for (int n = 0; n < 2; ++n) {
;             const int c = wc * 32 + n * 16 + fq * 4;
;             uint2 pu = make_uint2(0u, 0u), nu = make_uint2(0u, 0u);
;             if (pos != 0) pu = *(const uint2*)(Gs + (lr - 1) * 264 + c * 2);
;             if (pos != L - 1) nu = *(const uint2*)(Gs + (lr + 1) * 264 + c * 2);
;             f32x4 g = acc[ai][0][m][n], v = acc[ai][1][m][n];
;             float g0 = w0[n].x * lo2f(pu.x) + w1[n].x * (g[0] * s) + w2[n].x * lo2f(nu.x) + bb[n].x;
;             float g1 = w0[n].y * hi2f(pu.x) + w1[n].y * (g[1] * s) + w2[n].y * hi2f(nu.x) + bb[n].y;
;             float g2 = w0[n].z * lo2f(pu.y) + w1[n].z * (g[2] * s) + w2[n].z * lo2f(nu.y) + bb[n].z;
;             float g3 = w0[n].w * hi2f(pu.y) + w1[n].w * (g[3] * s) + w2[n].w * hi2f(nu.y) + bb[n].w;
;             uint2 o;
;             o.x = pack2(gelu_f(g0) * (v[0] * s), gelu_f(g1) * (v[1] * s));
;             o.y = pack2(gelu_f(g2) * (v[2] * s), gelu_f(g3) * (v[3] * s));
;             *(uint2*)(arow + ecol + c) = o;
.LBB0_436:
	s_or_b64 exec, exec, s[16:17]
	v_or_b32_e32 v74, 48, v163
	v_add_u32_e32 v0, s26, v74
	v_cmp_gt_i32_e64 s[4:5], s36, v0
	s_nop 1
	v_cndmask_b32_e64 v75, v224, v225, s[4:5]
	v_and_b32_e32 v76, v75, v0
	v_cmp_eq_u32_e64 s[6:7], 0, v76
	v_cmp_ne_u32_e64 s[4:5], 0, v76
	s_or_b64 s[6:7], vcc, s[6:7]
	s_and_saveexec_b64 s[10:11], s[6:7]
	s_cbranch_execz .LBB0_447
	s_movk_i32 s6, 0xff
	v_cmp_gt_i32_e64 s[6:7], s6, v74
	v_cmp_eq_u32_e64 s[8:9], v76, v75
	v_cmp_ne_u32_e32 vcc, v76, v75
	s_or_b64 s[6:7], s[6:7], s[8:9]
	s_and_b64 exec, exec, s[6:7]
	s_cbranch_execz .LBB0_447
	v_add_u32_e32 v78, 0xfffffef8, v171
	v_mov_b32_e32 v74, 0
	v_mov_b32_e32 v76, 0
	v_mov_b32_e32 v77, 0
	s_and_saveexec_b64 s[6:7], s[4:5]
	v_lshl_add_u32 v75, v165, 1, v78
	ds_read_b64 v[76:77], v75
	s_or_b64 exec, exec, s[6:7]
	v_mov_b32_e32 v75, 0
	s_and_saveexec_b64 s[6:7], vcc
	v_lshl_add_u32 v74, v165, 1, v171
	ds_read_b64 v[74:75], v74 offset:264
	s_or_b64 exec, exec, s[6:7]
	s_waitcnt lgkmcnt(0)
	v_lshlrev_b32_e32 v82, 16, v76
	v_and_b32_e32 v83, 0xffff0000, v76
	s_waitcnt vmcnt(5)
	v_pk_mul_f32 v[82:83], v[50:51], v[82:83]
	v_lshlrev_b32_e32 v84, 16, v74
	v_pk_fma_f32 v[82:83], v[42:43], v[178:179], v[82:83]
	v_and_b32_e32 v85, 0xffff0000, v74
	v_pk_fma_f32 v[82:83], v[46:47], v[84:85], v[82:83]
	v_mov_b64_e32 v[80:81], s[2:3]
	s_waitcnt vmcnt(3)
	v_pk_add_f32 v[82:83], v[54:55], v[82:83]
	s_movk_i32 s6, 0x1600
	v_pk_mul_f32 v[84:85], v[82:83], v[82:83]
	v_mad_i64_i32 v[80:81], s[6:7], v0, s6, v[80:81]
	v_mov_b32_e32 v173, v172
	v_pk_mul_f32 v[70:71], v[70:71], v[172:173]
	v_lshlrev_b32_e32 v76, 16, v77
	v_and_b32_e32 v77, 0xffff0000, v77
	v_pk_mul_f32 v[72:73], v[72:73], v[172:173]
	v_pk_fma_f32 v[84:85], v[84:85], v[246:247], v[248:249]
	s_nop 0
	v_pk_mul_f32 v[84:85], v[84:85], v[82:83] neg_lo:[0,1] neg_hi:[0,1]
	s_nop 0
	v_exp_f32_e32 v84, v84
	v_exp_f32_e32 v85, v85
	s_nop 0
	v_pk_add_f32 v[84:85], v[84:85], v[250:251]
	s_nop 0
	v_rcp_f32_e32 v84, v84
	v_rcp_f32_e32 v85, v85
	s_nop 0
	s_nop 0
	v_pk_mul_f32 v[82:83], v[82:83], v[84:85]
	s_nop 0
	v_pk_mul_f32 v[70:71], v[70:71], v[82:83]
	s_nop 0
	v_cvt_pk_bf16_f32 v74, v70, v71
	v_pk_mul_f32 v[70:71], v[52:53], v[76:77]
	v_lshlrev_b32_e32 v76, 16, v75
	v_pk_fma_f32 v[70:71], v[44:45], v[176:177], v[70:71]
	v_and_b32_e32 v77, 0xffff0000, v75
	v_pk_fma_f32 v[70:71], v[48:49], v[76:77], v[70:71]
	s_nop 0
	v_pk_add_f32 v[70:71], v[56:57], v[70:71]
	s_nop 0
	v_pk_mul_f32 v[76:77], v[70:71], v[70:71]
	s_nop 0
	s_nop 0
	s_nop 0
	v_pk_fma_f32 v[76:77], v[76:77], v[246:247], v[248:249]
	s_nop 0
	v_pk_mul_f32 v[76:77], v[76:77], v[70:71] neg_lo:[0,1] neg_hi:[0,1]
	s_nop 0
	v_exp_f32_e32 v76, v76
	v_exp_f32_e32 v77, v77
	s_nop 0
	v_pk_add_f32 v[76:77], v[76:77], v[250:251]
	s_nop 0
	v_rcp_f32_e32 v76, v76
	v_rcp_f32_e32 v77, v77
	s_nop 0
	v_lshlrev_b32_e32 v0, 1, v165
	v_pk_mul_f32 v[70:71], v[70:71], v[76:77]
	s_nop 0
	v_pk_mul_f32 v[70:71], v[72:73], v[70:71]
	v_mov_b32_e32 v72, 0
	v_cvt_pk_bf16_f32 v75, v70, v71
	v_lshl_add_u64 v[70:71], v[80:81], 0, v[0:1]
	global_store_dwordx2 v[70:71], v[74:75], off
	v_or_b32_e32 v0, 16, v165
	v_mov_b32_e32 v74, 0
	v_mov_b32_e32 v75, 0
	s_and_saveexec_b64 s[6:7], s[4:5]
	v_lshl_add_u32 v73, v0, 1, v78
	ds_read_b64 v[74:75], v73
	s_or_b64 exec, exec, s[6:7]
	v_mov_b32_e32 v73, 0
	s_and_saveexec_b64 s[4:5], vcc
	v_lshl_add_u32 v0, v0, 1, v171
	ds_read_b64 v[72:73], v0 offset:264
	s_or_b64 exec, exec, s[4:5]
	s_waitcnt lgkmcnt(0)
	v_lshlrev_b32_e32 v76, 16, v74
	v_and_b32_e32 v77, 0xffff0000, v74
	v_pk_mul_f32 v[76:77], v[26:27], v[76:77]
	v_lshlrev_b32_e32 v78, 16, v72
	s_waitcnt vmcnt(2)
	v_pk_fma_f32 v[76:77], v[38:39], v[134:135], v[76:77]
	v_and_b32_e32 v79, 0xffff0000, v72
	s_waitcnt vmcnt(1)
	v_pk_fma_f32 v[76:77], v[34:35], v[78:79], v[76:77]
	v_lshlrev_b32_e32 v74, 16, v75
	v_pk_add_f32 v[76:77], v[30:31], v[76:77]
	v_and_b32_e32 v75, 0xffff0000, v75
	v_pk_mul_f32 v[78:79], v[76:77], v[76:77]
	v_pk_mul_f32 v[74:75], v[28:29], v[74:75]
	v_pk_fma_f32 v[74:75], v[40:41], v[132:133], v[74:75]
	v_lshlrev_b32_e32 v72, 16, v73
	v_and_b32_e32 v73, 0xffff0000, v73
	v_pk_fma_f32 v[72:73], v[36:37], v[72:73], v[74:75]
	v_pk_mul_f32 v[66:67], v[66:67], v[172:173]
	v_pk_add_f32 v[72:73], v[32:33], v[72:73]
	v_pk_mul_f32 v[74:75], v[72:73], v[72:73]
	v_pk_fma_f32 v[78:79], v[78:79], v[246:247], v[248:249]
	s_nop 0
	v_pk_mul_f32 v[78:79], v[78:79], v[76:77] neg_lo:[0,1] neg_hi:[0,1]
	s_nop 0
	v_exp_f32_e32 v78, v78
	v_exp_f32_e32 v79, v79
	s_nop 0
	v_pk_add_f32 v[78:79], v[78:79], v[250:251]
	s_nop 0
	v_rcp_f32_e32 v78, v78
	v_rcp_f32_e32 v79, v79
	s_nop 0
	v_pk_mul_f32 v[76:77], v[76:77], v[78:79]
	v_pk_mul_f32 v[68:69], v[68:69], v[172:173]
	v_pk_mul_f32 v[66:67], v[66:67], v[76:77]
	v_cvt_pk_bf16_f32 v66, v66, v67
	v_pk_fma_f32 v[74:75], v[74:75], v[246:247], v[248:249]
	s_nop 0
	v_pk_mul_f32 v[74:75], v[74:75], v[72:73] neg_lo:[0,1] neg_hi:[0,1]
	s_nop 0
	v_exp_f32_e32 v74, v74
	v_exp_f32_e32 v75, v75
	s_nop 0
	v_pk_add_f32 v[74:75], v[74:75], v[250:251]
	s_nop 0
	v_rcp_f32_e32 v74, v74
	v_rcp_f32_e32 v75, v75
	s_nop 0
	s_nop 0
	v_pk_mul_f32 v[72:73], v[72:73], v[74:75]
	s_nop 0
	v_pk_mul_f32 v[68:69], v[68:69], v[72:73]
	s_nop 0
	v_cvt_pk_bf16_f32 v67, v68, v69
	global_store_dwordx2 v[70:71], v[66:67], off offset:32
; __device__ __forceinline__ float lo2f(unsigned u) { return __uint_as_float(u << 16); }
; __device__ __forceinline__ float hi2f(unsigned u) { return __uint_as_float(u & 0xffff0000u); }
; __device__ __forceinline__ float gelu_f(float x) {
;   const float c2 = 2.f * 0.7978845608028654f * 1.4426950408889634f;
;   float p = __builtin_fmaf(x * x, 0.044715f * c2, c2);
;   float e = __builtin_amdgcn_exp2f(-x * p);
;   return x * __builtin_amdgcn_rcpf(1.f + e);
; template <int MODE>
; __device__ __forceinline__ void gemm_tile(const int ph, const int which, const int pm, const int pn) {
;     ...
;       for (int m = 0; m < 4; ++m) {
;         const int lr = ai * HALF + wr * 64 + m * 16 + fr;
;         const int gr = browC + lr;
;         const int L = gr < 32768 ? 2048 : 4096;
;         const int pos = gr & (L - 1);
;         if ((lr >= 1 || pos == 0) && (lr <= 254 || pos == L - 1)) {
;           const float s = rsv[ai][m];
;           bf16_t* arow = C + (size_t)gr * DFF;
;   #pragma unroll
;         for (int n = 0; n < 2; ++n) {
;             const int c = wc * 32 + n * 16 + fq * 4;
;             uint2 pu = make_uint2(0u, 0u), nu = make_uint2(0u, 0u);
;             if (pos != 0) pu = *(const uint2*)(Gs + (lr - 1) * 264 + c * 2);
;             if (pos != L - 1) nu = *(const uint2*)(Gs + (lr + 1) * 264 + c * 2);
;             f32x4 g = acc[ai][0][m][n], v = acc[ai][1][m][n];
;             float g0 = w0[n].x * lo2f(pu.x) + w1[n].x * (g[0] * s) + w2[n].x * lo2f(nu.x) + bb[n].x;
;             float g1 = w0[n].y * hi2f(pu.x) + w1[n].y * (g[1] * s) + w2[n].y * hi2f(nu.x) + bb[n].y;
;             float g2 = w0[n].z * lo2f(pu.y) + w1[n].z * (g[2] * s) + w2[n].z * lo2f(nu.y) + bb[n].z;
;             float g3 = w0[n].w * hi2f(pu.y) + w1[n].w * (g[3] * s) + w2[n].w * hi2f(nu.y) + bb[n].w;
;             uint2 o;
;             o.x = pack2(gelu_f(g0) * (v[0] * s), gelu_f(g1) * (v[1] * s));
;             o.y = pack2(gelu_f(g2) * (v[2] * s), gelu_f(g3) * (v[3] * s));
;             *(uint2*)(arow + ecol + c) = o;
.LBB0_447:
	s_or_b64 exec, exec, s[10:11]
	v_add_u32_e32 v0, 0x80, v164
	v_cmp_gt_i32_e32 vcc, s36, v0
	s_movk_i32 s4, 0xff80
	s_nop 0
	v_cndmask_b32_e32 v66, v224, v225, vcc
	v_and_b32_e32 v67, v66, v0
	v_cmp_lt_i32_e32 vcc, s4, v163
	v_cmp_eq_u32_e64 s[6:7], 0, v67
	v_cmp_ne_u32_e64 s[4:5], 0, v67
	s_or_b64 s[6:7], vcc, s[6:7]
	s_and_saveexec_b64 s[10:11], s[6:7]
	s_cbranch_execz .LBB0_458
	s_movk_i32 s6, 0x7f
	v_cmp_gt_i32_e64 s[6:7], s6, v163
	v_cmp_eq_u32_e64 s[8:9], v67, v66
	v_cmp_ne_u32_e32 vcc, v67, v66
	s_or_b64 s[6:7], s[6:7], s[8:9]
	s_and_b64 exec, exec, s[6:7]
	s_cbranch_execz .LBB0_458
	v_add_u32_e32 v70, 0xfffffef8, v169
	v_mov_b32_e32 v66, 0
	v_mov_b32_e32 v68, 0
	v_mov_b32_e32 v69, 0
	s_and_saveexec_b64 s[6:7], s[4:5]
	v_lshl_add_u32 v67, v165, 1, v70
	ds_read_b64 v[68:69], v67
	s_or_b64 exec, exec, s[6:7]
	v_mov_b32_e32 v67, 0
	s_and_saveexec_b64 s[6:7], vcc
	v_lshl_add_u32 v66, v165, 1, v169
	ds_read_b64 v[66:67], v66 offset:264
	s_or_b64 exec, exec, s[6:7]
	s_waitcnt lgkmcnt(0)
	v_lshlrev_b32_e32 v74, 16, v68
	v_and_b32_e32 v75, 0xffff0000, v68
	s_waitcnt vmcnt(5)
	v_pk_mul_f32 v[74:75], v[50:51], v[74:75]
	v_lshlrev_b32_e32 v76, 16, v66
	v_pk_fma_f32 v[74:75], v[42:43], v[130:131], v[74:75]
	v_and_b32_e32 v77, 0xffff0000, v66
	v_pk_fma_f32 v[74:75], v[46:47], v[76:77], v[74:75]
	v_mov_b64_e32 v[72:73], s[2:3]
	s_waitcnt vmcnt(3)
	v_pk_add_f32 v[74:75], v[54:55], v[74:75]
	s_movk_i32 s6, 0x1600
	v_pk_mul_f32 v[76:77], v[74:75], v[74:75]
	v_mad_i64_i32 v[72:73], s[6:7], v0, s6, v[72:73]
	v_mov_b32_e32 v171, v170
	v_pk_mul_f32 v[62:63], v[62:63], v[170:171]
	v_lshlrev_b32_e32 v68, 16, v69
	v_and_b32_e32 v69, 0xffff0000, v69
	v_pk_mul_f32 v[64:65], v[64:65], v[170:171]
	v_pk_fma_f32 v[76:77], v[76:77], v[246:247], v[248:249]
	s_nop 0
	v_pk_mul_f32 v[76:77], v[76:77], v[74:75] neg_lo:[0,1] neg_hi:[0,1]
	s_nop 0
	v_exp_f32_e32 v76, v76
	v_exp_f32_e32 v77, v77
	s_nop 0
	v_pk_add_f32 v[76:77], v[76:77], v[250:251]
	s_nop 0
	v_rcp_f32_e32 v76, v76
	v_rcp_f32_e32 v77, v77
	s_nop 0
	s_nop 0
	v_pk_mul_f32 v[74:75], v[74:75], v[76:77]
	s_nop 0
	v_pk_mul_f32 v[62:63], v[62:63], v[74:75]
	s_nop 0
	v_cvt_pk_bf16_f32 v66, v62, v63
	v_pk_mul_f32 v[62:63], v[52:53], v[68:69]
	v_lshlrev_b32_e32 v68, 16, v67
	v_pk_fma_f32 v[62:63], v[44:45], v[128:129], v[62:63]
	v_and_b32_e32 v69, 0xffff0000, v67
	v_pk_fma_f32 v[62:63], v[48:49], v[68:69], v[62:63]
	s_nop 0
	v_pk_add_f32 v[62:63], v[56:57], v[62:63]
	s_nop 0
	v_pk_mul_f32 v[68:69], v[62:63], v[62:63]
	s_nop 0
	s_nop 0
	s_nop 0
	v_pk_fma_f32 v[68:69], v[68:69], v[246:247], v[248:249]
	s_nop 0
	v_pk_mul_f32 v[68:69], v[68:69], v[62:63] neg_lo:[0,1] neg_hi:[0,1]
	s_nop 0
	v_exp_f32_e32 v68, v68
	v_exp_f32_e32 v69, v69
	s_nop 0
	v_pk_add_f32 v[68:69], v[68:69], v[250:251]
	s_nop 0
	v_rcp_f32_e32 v68, v68
	v_rcp_f32_e32 v69, v69
	s_nop 0
	v_lshlrev_b32_e32 v0, 1, v165
	v_pk_mul_f32 v[62:63], v[62:63], v[68:69]
	s_nop 0
	v_pk_mul_f32 v[62:63], v[64:65], v[62:63]
	v_mov_b32_e32 v64, 0
	v_cvt_pk_bf16_f32 v67, v62, v63
	v_lshl_add_u64 v[62:63], v[72:73], 0, v[0:1]
	global_store_dwordx2 v[62:63], v[66:67], off
	v_or_b32_e32 v0, 16, v165
	v_mov_b32_e32 v66, 0
	v_mov_b32_e32 v67, 0
	s_and_saveexec_b64 s[6:7], s[4:5]
	v_lshl_add_u32 v65, v0, 1, v70
	ds_read_b64 v[66:67], v65
	s_or_b64 exec, exec, s[6:7]
	v_mov_b32_e32 v65, 0
	s_and_saveexec_b64 s[4:5], vcc
	v_lshl_add_u32 v0, v0, 1, v169
	ds_read_b64 v[64:65], v0 offset:264
	s_or_b64 exec, exec, s[4:5]
	s_waitcnt lgkmcnt(0)
	v_lshlrev_b32_e32 v68, 16, v66
	v_and_b32_e32 v69, 0xffff0000, v66
	v_pk_mul_f32 v[68:69], v[26:27], v[68:69]
	v_lshlrev_b32_e32 v70, 16, v64
	s_waitcnt vmcnt(2)
	v_pk_fma_f32 v[68:69], v[38:39], v[126:127], v[68:69]
	v_and_b32_e32 v71, 0xffff0000, v64
	s_waitcnt vmcnt(1)
	v_pk_fma_f32 v[68:69], v[34:35], v[70:71], v[68:69]
	v_lshlrev_b32_e32 v66, 16, v67
	v_pk_add_f32 v[68:69], v[30:31], v[68:69]
	v_and_b32_e32 v67, 0xffff0000, v67
	v_pk_mul_f32 v[70:71], v[68:69], v[68:69]
	v_pk_mul_f32 v[66:67], v[28:29], v[66:67]
	v_pk_fma_f32 v[66:67], v[40:41], v[124:125], v[66:67]
	v_lshlrev_b32_e32 v64, 16, v65
	v_and_b32_e32 v65, 0xffff0000, v65
	v_pk_fma_f32 v[64:65], v[36:37], v[64:65], v[66:67]
	v_pk_mul_f32 v[58:59], v[58:59], v[170:171]
	v_pk_add_f32 v[64:65], v[32:33], v[64:65]
	v_pk_mul_f32 v[66:67], v[64:65], v[64:65]
	v_pk_fma_f32 v[70:71], v[70:71], v[246:247], v[248:249]
	s_nop 0
	v_pk_mul_f32 v[70:71], v[70:71], v[68:69] neg_lo:[0,1] neg_hi:[0,1]
	s_nop 0
	v_exp_f32_e32 v70, v70
	v_exp_f32_e32 v71, v71
	s_nop 0
	v_pk_add_f32 v[70:71], v[70:71], v[250:251]
	s_nop 0
	v_rcp_f32_e32 v70, v70
	v_rcp_f32_e32 v71, v71
	s_nop 0
	v_pk_mul_f32 v[68:69], v[68:69], v[70:71]
	v_pk_mul_f32 v[60:61], v[60:61], v[170:171]
	v_pk_mul_f32 v[58:59], v[58:59], v[68:69]
	v_cvt_pk_bf16_f32 v58, v58, v59
	v_pk_fma_f32 v[66:67], v[66:67], v[246:247], v[248:249]
	s_nop 0
	v_pk_mul_f32 v[66:67], v[66:67], v[64:65] neg_lo:[0,1] neg_hi:[0,1]
	s_nop 0
	v_exp_f32_e32 v66, v66
	v_exp_f32_e32 v67, v67
	s_nop 0
	v_pk_add_f32 v[66:67], v[66:67], v[250:251]
	s_nop 0
	v_rcp_f32_e32 v66, v66
	v_rcp_f32_e32 v67, v67
	s_nop 0
	s_nop 0
	v_pk_mul_f32 v[64:65], v[64:65], v[66:67]
	s_nop 0
	v_pk_mul_f32 v[60:61], v[60:61], v[64:65]
	s_nop 0
	v_cvt_pk_bf16_f32 v59, v60, v61
	global_store_dwordx2 v[62:63], v[58:59], off offset:32
; __device__ __forceinline__ float lo2f(unsigned u) { return __uint_as_float(u << 16); }
; __device__ __forceinline__ float hi2f(unsigned u) { return __uint_as_float(u & 0xffff0000u); }
; __device__ __forceinline__ float gelu_f(float x) {
;   const float c2 = 2.f * 0.7978845608028654f * 1.4426950408889634f;
;   float p = __builtin_fmaf(x * x, 0.044715f * c2, c2);
;   float e = __builtin_amdgcn_exp2f(-x * p);
;   return x * __builtin_amdgcn_rcpf(1.f + e);
; template <int MODE>
; __device__ __forceinline__ void gemm_tile(const int ph, const int which, const int pm, const int pn) {
;     ...
;       for (int m = 0; m < 4; ++m) {
;         const int lr = ai * HALF + wr * 64 + m * 16 + fr;
;         const int gr = browC + lr;
;         const int L = gr < 32768 ? 2048 : 4096;
;         const int pos = gr & (L - 1);
;         if ((lr >= 1 || pos == 0) && (lr <= 254 || pos == L - 1)) {
;           const float s = rsv[ai][m];
;           bf16_t* arow = C + (size_t)gr * DFF;
;   #pragma unroll
;         for (int n = 0; n < 2; ++n) {
;             const int c = wc * 32 + n * 16 + fq * 4;
;             uint2 pu = make_uint2(0u, 0u), nu = make_uint2(0u, 0u);
;             if (pos != 0) pu = *(const uint2*)(Gs + (lr - 1) * 264 + c * 2);
;             if (pos != L - 1) nu = *(const uint2*)(Gs + (lr + 1) * 264 + c * 2);
;             f32x4 g = acc[ai][0][m][n], v = acc[ai][1][m][n];
;             float g0 = w0[n].x * lo2f(pu.x) + w1[n].x * (g[0] * s) + w2[n].x * lo2f(nu.x) + bb[n].x;
;             float g1 = w0[n].y * hi2f(pu.x) + w1[n].y * (g[1] * s) + w2[n].y * hi2f(nu.x) + bb[n].y;
;             float g2 = w0[n].z * lo2f(pu.y) + w1[n].z * (g[2] * s) + w2[n].z * lo2f(nu.y) + bb[n].z;
;             float g3 = w0[n].w * hi2f(pu.y) + w1[n].w * (g[3] * s) + w2[n].w * hi2f(nu.y) + bb[n].w;
;             uint2 o;
;             o.x = pack2(gelu_f(g0) * (v[0] * s), gelu_f(g1) * (v[1] * s));
;             o.y = pack2(gelu_f(g2) * (v[2] * s), gelu_f(g3) * (v[3] * s));
;             *(uint2*)(arow + ecol + c) = o;
.LBB0_458:
	s_or_b64 exec, exec, s[10:11]
	v_add_u32_e32 v0, 0x90, v164
	v_cmp_gt_i32_e32 vcc, s36, v0
	s_movk_i32 s4, 0xff70
	s_nop 0
	v_cndmask_b32_e32 v58, v224, v225, vcc
	v_and_b32_e32 v59, v58, v0
	v_cmp_lt_i32_e32 vcc, s4, v163
	v_cmp_eq_u32_e64 s[6:7], 0, v59
	v_cmp_ne_u32_e64 s[4:5], 0, v59
	s_or_b64 s[6:7], vcc, s[6:7]
	s_and_saveexec_b64 s[10:11], s[6:7]
	s_cbranch_execz .LBB0_469
	s_movk_i32 s6, 0x6f
	v_cmp_gt_i32_e64 s[6:7], s6, v163
	v_cmp_eq_u32_e64 s[8:9], v59, v58
	v_cmp_ne_u32_e32 vcc, v59, v58
	s_or_b64 s[6:7], s[6:7], s[8:9]
	s_and_b64 exec, exec, s[6:7]
	s_cbranch_execz .LBB0_469
	v_add_u32_e32 v62, 0xfffffef8, v154
	v_mov_b32_e32 v58, 0
	v_mov_b32_e32 v60, 0
	v_mov_b32_e32 v61, 0
	s_and_saveexec_b64 s[6:7], s[4:5]
	v_lshl_add_u32 v59, v165, 1, v62
	ds_read_b64 v[60:61], v59
	s_or_b64 exec, exec, s[6:7]
	v_mov_b32_e32 v59, 0
	s_and_saveexec_b64 s[6:7], vcc
	v_lshl_add_u32 v58, v165, 1, v154
	ds_read_b64 v[58:59], v58 offset:264
	s_or_b64 exec, exec, s[6:7]
	s_waitcnt lgkmcnt(0)
	v_lshlrev_b32_e32 v66, 16, v60
	v_and_b32_e32 v67, 0xffff0000, v60
	s_waitcnt vmcnt(5)
	v_pk_mul_f32 v[66:67], v[50:51], v[66:67]
	v_lshlrev_b32_e32 v68, 16, v58
	v_pk_fma_f32 v[66:67], v[42:43], v[122:123], v[66:67]
	v_and_b32_e32 v69, 0xffff0000, v58
	v_pk_fma_f32 v[66:67], v[46:47], v[68:69], v[66:67]
	v_mov_b64_e32 v[64:65], s[2:3]
	s_waitcnt vmcnt(3)
	v_pk_add_f32 v[66:67], v[54:55], v[66:67]
	s_movk_i32 s6, 0x1600
	v_pk_mul_f32 v[68:69], v[66:67], v[66:67]
	v_mad_i64_i32 v[64:65], s[6:7], v0, s6, v[64:65]
	v_mov_b32_e32 v169, v168
	v_pk_mul_f32 v[22:23], v[22:23], v[168:169]
	v_lshlrev_b32_e32 v60, 16, v61
	v_and_b32_e32 v61, 0xffff0000, v61
	v_pk_mul_f32 v[24:25], v[24:25], v[168:169]
	v_pk_fma_f32 v[68:69], v[68:69], v[246:247], v[248:249]
	s_nop 0
	v_pk_mul_f32 v[68:69], v[68:69], v[66:67] neg_lo:[0,1] neg_hi:[0,1]
	s_nop 0
	v_exp_f32_e32 v68, v68
	v_exp_f32_e32 v69, v69
	s_nop 0
	v_pk_add_f32 v[68:69], v[68:69], v[250:251]
	s_nop 0
	v_rcp_f32_e32 v68, v68
	v_rcp_f32_e32 v69, v69
	s_nop 0
	s_nop 0
	v_pk_mul_f32 v[66:67], v[66:67], v[68:69]
	s_nop 0
	v_pk_mul_f32 v[22:23], v[22:23], v[66:67]
	s_nop 0
	v_cvt_pk_bf16_f32 v58, v22, v23
	v_pk_mul_f32 v[22:23], v[52:53], v[60:61]
	v_lshlrev_b32_e32 v60, 16, v59
	v_pk_fma_f32 v[22:23], v[44:45], v[120:121], v[22:23]
	v_and_b32_e32 v61, 0xffff0000, v59
	v_pk_fma_f32 v[22:23], v[48:49], v[60:61], v[22:23]
	s_nop 0
	v_pk_add_f32 v[22:23], v[56:57], v[22:23]
	s_nop 0
	v_pk_mul_f32 v[60:61], v[22:23], v[22:23]
	s_nop 0
	s_nop 0
	s_nop 0
	v_pk_fma_f32 v[60:61], v[60:61], v[246:247], v[248:249]
	s_nop 0
	v_pk_mul_f32 v[60:61], v[60:61], v[22:23] neg_lo:[0,1] neg_hi:[0,1]
	s_nop 0
	v_exp_f32_e32 v60, v60
	v_exp_f32_e32 v61, v61
	s_nop 0
	v_pk_add_f32 v[60:61], v[60:61], v[250:251]
	s_nop 0
	v_rcp_f32_e32 v60, v60
	v_rcp_f32_e32 v61, v61
	s_nop 0
	v_lshlrev_b32_e32 v0, 1, v165
	v_pk_mul_f32 v[22:23], v[22:23], v[60:61]
	s_nop 0
	v_pk_mul_f32 v[22:23], v[24:25], v[22:23]
	v_mov_b32_e32 v24, 0
	v_cvt_pk_bf16_f32 v59, v22, v23
	v_lshl_add_u64 v[22:23], v[64:65], 0, v[0:1]
	global_store_dwordx2 v[22:23], v[58:59], off
	v_or_b32_e32 v0, 16, v165
	v_mov_b32_e32 v58, 0
	v_mov_b32_e32 v59, 0
	s_and_saveexec_b64 s[6:7], s[4:5]
	v_lshl_add_u32 v25, v0, 1, v62
	ds_read_b64 v[58:59], v25
	s_or_b64 exec, exec, s[6:7]
	v_mov_b32_e32 v25, 0
	s_and_saveexec_b64 s[4:5], vcc
	v_lshl_add_u32 v0, v0, 1, v154
	ds_read_b64 v[24:25], v0 offset:264
	s_or_b64 exec, exec, s[4:5]
	s_waitcnt lgkmcnt(0)
	v_lshlrev_b32_e32 v60, 16, v58
	v_and_b32_e32 v61, 0xffff0000, v58
	v_pk_mul_f32 v[60:61], v[26:27], v[60:61]
	v_lshlrev_b32_e32 v62, 16, v24
	s_waitcnt vmcnt(2)
	v_pk_fma_f32 v[60:61], v[38:39], v[118:119], v[60:61]
	v_and_b32_e32 v63, 0xffff0000, v24
	s_waitcnt vmcnt(1)
	v_pk_fma_f32 v[60:61], v[34:35], v[62:63], v[60:61]
	v_lshlrev_b32_e32 v58, 16, v59
	v_pk_add_f32 v[60:61], v[30:31], v[60:61]
	v_and_b32_e32 v59, 0xffff0000, v59
	v_pk_mul_f32 v[62:63], v[60:61], v[60:61]
	v_pk_mul_f32 v[58:59], v[28:29], v[58:59]
	v_pk_fma_f32 v[58:59], v[40:41], v[116:117], v[58:59]
	v_lshlrev_b32_e32 v24, 16, v25
	v_and_b32_e32 v25, 0xffff0000, v25
	v_pk_fma_f32 v[24:25], v[36:37], v[24:25], v[58:59]
	v_pk_mul_f32 v[18:19], v[18:19], v[168:169]
	v_pk_add_f32 v[24:25], v[32:33], v[24:25]
	v_pk_mul_f32 v[58:59], v[24:25], v[24:25]
	v_pk_fma_f32 v[62:63], v[62:63], v[246:247], v[248:249]
	s_nop 0
	v_pk_mul_f32 v[62:63], v[62:63], v[60:61] neg_lo:[0,1] neg_hi:[0,1]
	s_nop 0
	v_exp_f32_e32 v62, v62
	v_exp_f32_e32 v63, v63
	s_nop 0
	v_pk_add_f32 v[62:63], v[62:63], v[250:251]
	s_nop 0
	v_rcp_f32_e32 v62, v62
	v_rcp_f32_e32 v63, v63
	s_nop 0
	v_pk_mul_f32 v[60:61], v[60:61], v[62:63]
	v_pk_mul_f32 v[20:21], v[20:21], v[168:169]
	v_pk_mul_f32 v[18:19], v[18:19], v[60:61]
	v_cvt_pk_bf16_f32 v18, v18, v19
	v_pk_fma_f32 v[58:59], v[58:59], v[246:247], v[248:249]
	s_nop 0
	v_pk_mul_f32 v[58:59], v[58:59], v[24:25] neg_lo:[0,1] neg_hi:[0,1]
	s_nop 0
	v_exp_f32_e32 v58, v58
	v_exp_f32_e32 v59, v59
	s_nop 0
	v_pk_add_f32 v[58:59], v[58:59], v[250:251]
	s_nop 0
	v_rcp_f32_e32 v58, v58
	v_rcp_f32_e32 v59, v59
	s_nop 0
	s_nop 0
	v_pk_mul_f32 v[24:25], v[24:25], v[58:59]
	s_nop 0
	v_pk_mul_f32 v[20:21], v[20:21], v[24:25]
	s_nop 0
	v_cvt_pk_bf16_f32 v19, v20, v21
	global_store_dwordx2 v[22:23], v[18:19], off offset:32
; __device__ __forceinline__ float lo2f(unsigned u) { return __uint_as_float(u << 16); }
; __device__ __forceinline__ float hi2f(unsigned u) { return __uint_as_float(u & 0xffff0000u); }
; __device__ __forceinline__ float gelu_f(float x) {
;   const float c2 = 2.f * 0.7978845608028654f * 1.4426950408889634f;
;   float p = __builtin_fmaf(x * x, 0.044715f * c2, c2);
;   float e = __builtin_amdgcn_exp2f(-x * p);
;   return x * __builtin_amdgcn_rcpf(1.f + e);
; template <int MODE>
; __device__ __forceinline__ void gemm_tile(const int ph, const int which, const int pm, const int pn) {
;     ...
;       for (int m = 0; m < 4; ++m) {
;         const int lr = ai * HALF + wr * 64 + m * 16 + fr;
;         const int gr = browC + lr;
;         const int L = gr < 32768 ? 2048 : 4096;
;         const int pos = gr & (L - 1);
;         if ((lr >= 1 || pos == 0) && (lr <= 254 || pos == L - 1)) {
;           const float s = rsv[ai][m];
;           bf16_t* arow = C + (size_t)gr * DFF;
;   #pragma unroll
;         for (int n = 0; n < 2; ++n) {
;             const int c = wc * 32 + n * 16 + fq * 4;
;             uint2 pu = make_uint2(0u, 0u), nu = make_uint2(0u, 0u);
;             if (pos != 0) pu = *(const uint2*)(Gs + (lr - 1) * 264 + c * 2);
;             if (pos != L - 1) nu = *(const uint2*)(Gs + (lr + 1) * 264 + c * 2);
;             f32x4 g = acc[ai][0][m][n], v = acc[ai][1][m][n];
;             float g0 = w0[n].x * lo2f(pu.x) + w1[n].x * (g[0] * s) + w2[n].x * lo2f(nu.x) + bb[n].x;
;             float g1 = w0[n].y * hi2f(pu.x) + w1[n].y * (g[1] * s) + w2[n].y * hi2f(nu.x) + bb[n].y;
;             float g2 = w0[n].z * lo2f(pu.y) + w1[n].z * (g[2] * s) + w2[n].z * lo2f(nu.y) + bb[n].z;
;             float g3 = w0[n].w * hi2f(pu.y) + w1[n].w * (g[3] * s) + w2[n].w * hi2f(nu.y) + bb[n].w;
;             uint2 o;
;             o.x = pack2(gelu_f(g0) * (v[0] * s), gelu_f(g1) * (v[1] * s));
;             o.y = pack2(gelu_f(g2) * (v[2] * s), gelu_f(g3) * (v[3] * s));
;             *(uint2*)(arow + ecol + c) = o;
.LBB0_469:
	s_or_b64 exec, exec, s[10:11]
	v_add_u32_e32 v0, 0xa0, v164
	v_cmp_gt_i32_e32 vcc, s36, v0
	s_movk_i32 s4, 0xff60
	s_nop 0
	v_cndmask_b32_e32 v18, v224, v225, vcc
	v_and_b32_e32 v19, v18, v0
	v_cmp_lt_i32_e32 vcc, s4, v163
	v_cmp_eq_u32_e64 s[6:7], 0, v19
	v_cmp_ne_u32_e64 s[4:5], 0, v19
	s_or_b64 s[6:7], vcc, s[6:7]
	s_and_saveexec_b64 s[10:11], s[6:7]
	s_cbranch_execz .LBB0_480
	s_movk_i32 s6, 0x5f
	v_cmp_gt_i32_e64 s[6:7], s6, v163
	v_cmp_eq_u32_e64 s[8:9], v19, v18
	v_cmp_ne_u32_e32 vcc, v19, v18
	s_or_b64 s[6:7], s[6:7], s[8:9]
	s_and_b64 exec, exec, s[6:7]
	s_cbranch_execz .LBB0_480
	v_add_u32_e32 v22, 0xfffffef8, v146
	v_mov_b32_e32 v18, 0
	v_mov_b32_e32 v20, 0
	v_mov_b32_e32 v21, 0
	s_and_saveexec_b64 s[6:7], s[4:5]
	v_lshl_add_u32 v19, v165, 1, v22
	ds_read_b64 v[20:21], v19
	s_or_b64 exec, exec, s[6:7]
	v_mov_b32_e32 v19, 0
	s_and_saveexec_b64 s[6:7], vcc
	v_lshl_add_u32 v18, v165, 1, v146
	ds_read_b64 v[18:19], v18 offset:264
	s_or_b64 exec, exec, s[6:7]
	s_waitcnt lgkmcnt(0)
	v_lshlrev_b32_e32 v58, 16, v20
	v_and_b32_e32 v59, 0xffff0000, v20
	s_waitcnt vmcnt(5)
	v_pk_mul_f32 v[58:59], v[50:51], v[58:59]
	v_lshlrev_b32_e32 v60, 16, v18
	v_pk_fma_f32 v[58:59], v[42:43], v[114:115], v[58:59]
	v_and_b32_e32 v61, 0xffff0000, v18
	v_pk_fma_f32 v[58:59], v[46:47], v[60:61], v[58:59]
	v_mov_b64_e32 v[24:25], s[2:3]
	s_waitcnt vmcnt(3)
	v_pk_add_f32 v[58:59], v[54:55], v[58:59]
	s_movk_i32 s6, 0x1600
	v_pk_mul_f32 v[60:61], v[58:59], v[58:59]
	v_mad_i64_i32 v[24:25], s[6:7], v0, s6, v[24:25]
	v_mov_b32_e32 v167, v166
	v_pk_mul_f32 v[14:15], v[14:15], v[166:167]
	v_lshlrev_b32_e32 v20, 16, v21
	v_and_b32_e32 v21, 0xffff0000, v21
	v_pk_mul_f32 v[16:17], v[16:17], v[166:167]
	v_pk_fma_f32 v[60:61], v[60:61], v[246:247], v[248:249]
	s_nop 0
	v_pk_mul_f32 v[60:61], v[60:61], v[58:59] neg_lo:[0,1] neg_hi:[0,1]
	s_nop 0
	v_exp_f32_e32 v60, v60
	v_exp_f32_e32 v61, v61
	s_nop 0
	v_pk_add_f32 v[60:61], v[60:61], v[250:251]
	s_nop 0
	v_rcp_f32_e32 v60, v60
	v_rcp_f32_e32 v61, v61
	s_nop 0
	s_nop 0
	v_pk_mul_f32 v[58:59], v[58:59], v[60:61]
	s_nop 0
	v_pk_mul_f32 v[14:15], v[14:15], v[58:59]
	s_nop 0
	v_cvt_pk_bf16_f32 v18, v14, v15
	v_pk_mul_f32 v[14:15], v[52:53], v[20:21]
	v_lshlrev_b32_e32 v20, 16, v19
	v_pk_fma_f32 v[14:15], v[44:45], v[112:113], v[14:15]
	v_and_b32_e32 v21, 0xffff0000, v19
	v_pk_fma_f32 v[14:15], v[48:49], v[20:21], v[14:15]
	s_nop 0
	v_pk_add_f32 v[14:15], v[56:57], v[14:15]
	s_nop 0
	v_pk_mul_f32 v[20:21], v[14:15], v[14:15]
	s_nop 0
	s_nop 0
	s_nop 0
	v_pk_fma_f32 v[20:21], v[20:21], v[246:247], v[248:249]
	s_nop 0
	v_pk_mul_f32 v[20:21], v[20:21], v[14:15] neg_lo:[0,1] neg_hi:[0,1]
	s_nop 0
	v_exp_f32_e32 v20, v20
	v_exp_f32_e32 v21, v21
	s_nop 0
	v_pk_add_f32 v[20:21], v[20:21], v[250:251]
	s_nop 0
	v_rcp_f32_e32 v20, v20
	v_rcp_f32_e32 v21, v21
	s_nop 0
	v_lshlrev_b32_e32 v0, 1, v165
	v_pk_mul_f32 v[14:15], v[14:15], v[20:21]
	s_nop 0
	v_pk_mul_f32 v[14:15], v[16:17], v[14:15]
	v_mov_b32_e32 v16, 0
	v_cvt_pk_bf16_f32 v19, v14, v15
	v_lshl_add_u64 v[14:15], v[24:25], 0, v[0:1]
	global_store_dwordx2 v[14:15], v[18:19], off
	v_or_b32_e32 v0, 16, v165
	v_mov_b32_e32 v18, 0
	v_mov_b32_e32 v19, 0
	s_and_saveexec_b64 s[6:7], s[4:5]
	v_lshl_add_u32 v17, v0, 1, v22
	ds_read_b64 v[18:19], v17
	s_or_b64 exec, exec, s[6:7]
	v_mov_b32_e32 v17, 0
	s_and_saveexec_b64 s[4:5], vcc
	v_lshl_add_u32 v0, v0, 1, v146
	ds_read_b64 v[16:17], v0 offset:264
	s_or_b64 exec, exec, s[4:5]
	s_waitcnt lgkmcnt(0)
	v_lshlrev_b32_e32 v20, 16, v18
	v_and_b32_e32 v21, 0xffff0000, v18
	v_pk_mul_f32 v[20:21], v[26:27], v[20:21]
	v_lshlrev_b32_e32 v22, 16, v16
	s_waitcnt vmcnt(2)
	v_pk_fma_f32 v[20:21], v[38:39], v[110:111], v[20:21]
	v_and_b32_e32 v23, 0xffff0000, v16
	s_waitcnt vmcnt(1)
	v_pk_fma_f32 v[20:21], v[34:35], v[22:23], v[20:21]
	v_lshlrev_b32_e32 v18, 16, v19
	v_pk_add_f32 v[20:21], v[30:31], v[20:21]
	v_and_b32_e32 v19, 0xffff0000, v19
	v_pk_mul_f32 v[22:23], v[20:21], v[20:21]
	v_pk_mul_f32 v[18:19], v[28:29], v[18:19]
	v_pk_fma_f32 v[18:19], v[40:41], v[108:109], v[18:19]
	v_lshlrev_b32_e32 v16, 16, v17
	v_and_b32_e32 v17, 0xffff0000, v17
	v_pk_fma_f32 v[16:17], v[36:37], v[16:17], v[18:19]
	v_pk_mul_f32 v[10:11], v[10:11], v[166:167]
	v_pk_add_f32 v[16:17], v[32:33], v[16:17]
	v_pk_mul_f32 v[18:19], v[16:17], v[16:17]
	v_pk_fma_f32 v[22:23], v[22:23], v[246:247], v[248:249]
	s_nop 0
	v_pk_mul_f32 v[22:23], v[22:23], v[20:21] neg_lo:[0,1] neg_hi:[0,1]
	s_nop 0
	v_exp_f32_e32 v22, v22
	v_exp_f32_e32 v23, v23
	s_nop 0
	v_pk_add_f32 v[22:23], v[22:23], v[250:251]
	s_nop 0
	v_rcp_f32_e32 v22, v22
	v_rcp_f32_e32 v23, v23
	s_nop 0
	v_pk_mul_f32 v[20:21], v[20:21], v[22:23]
	v_pk_mul_f32 v[12:13], v[12:13], v[166:167]
	v_pk_mul_f32 v[10:11], v[10:11], v[20:21]
	v_cvt_pk_bf16_f32 v10, v10, v11
	v_pk_fma_f32 v[18:19], v[18:19], v[246:247], v[248:249]
	s_nop 0
	v_pk_mul_f32 v[18:19], v[18:19], v[16:17] neg_lo:[0,1] neg_hi:[0,1]
	s_nop 0
	v_exp_f32_e32 v18, v18
	v_exp_f32_e32 v19, v19
	s_nop 0
	v_pk_add_f32 v[18:19], v[18:19], v[250:251]
	s_nop 0
	v_rcp_f32_e32 v18, v18
	v_rcp_f32_e32 v19, v19
	s_nop 0
	s_nop 0
	v_pk_mul_f32 v[16:17], v[16:17], v[18:19]
	s_nop 0
	v_pk_mul_f32 v[12:13], v[12:13], v[16:17]
	s_nop 0
	v_cvt_pk_bf16_f32 v11, v12, v13
	global_store_dwordx2 v[14:15], v[10:11], off offset:32
; __device__ __forceinline__ float lo2f(unsigned u) { return __uint_as_float(u << 16); }
; __device__ __forceinline__ float hi2f(unsigned u) { return __uint_as_float(u & 0xffff0000u); }
; __device__ __forceinline__ float gelu_f(float x) {
;   const float c2 = 2.f * 0.7978845608028654f * 1.4426950408889634f;
;   float p = __builtin_fmaf(x * x, 0.044715f * c2, c2);
;   float e = __builtin_amdgcn_exp2f(-x * p);
;   return x * __builtin_amdgcn_rcpf(1.f + e);
; }
; template <int MODE>
; __device__ __forceinline__ void gemm_tile(const int ph, const int which, const int pm, const int pn) {
;     ...
;       for (int m = 0; m < 4; ++m) {
;         const int lr = ai * HALF + wr * 64 + m * 16 + fr;
;         const int gr = browC + lr;
;         const int L = gr < 32768 ? 2048 : 4096;
;         const int pos = gr & (L - 1);
;         if ((lr >= 1 || pos == 0) && (lr <= 254 || pos == L - 1)) {
;           const float s = rsv[ai][m];
;           bf16_t* arow = C + (size_t)gr * DFF;
;   #pragma unroll
;         for (int n = 0; n < 2; ++n) {
;             const int c = wc * 32 + n * 16 + fq * 4;
;             uint2 pu = make_uint2(0u, 0u), nu = make_uint2(0u, 0u);
;             if (pos != 0) pu = *(const uint2*)(Gs + (lr - 1) * 264 + c * 2);
;             if (pos != L - 1) nu = *(const uint2*)(Gs + (lr + 1) * 264 + c * 2);
;             f32x4 g = acc[ai][0][m][n], v = acc[ai][1][m][n];
;             float g0 = w0[n].x * lo2f(pu.x) + w1[n].x * (g[0] * s) + w2[n].x * lo2f(nu.x) + bb[n].x;
;             float g1 = w0[n].y * hi2f(pu.x) + w1[n].y * (g[1] * s) + w2[n].y * hi2f(nu.x) + bb[n].y;
;             float g2 = w0[n].z * lo2f(pu.y) + w1[n].z * (g[2] * s) + w2[n].z * lo2f(nu.y) + bb[n].z;
;             float g3 = w0[n].w * hi2f(pu.y) + w1[n].w * (g[3] * s) + w2[n].w * hi2f(nu.y) + bb[n].w;
;             uint2 o;
;             o.x = pack2(gelu_f(g0) * (v[0] * s), gelu_f(g1) * (v[1] * s));
;             o.y = pack2(gelu_f(g2) * (v[2] * s), gelu_f(g3) * (v[3] * s));
;             *(uint2*)(arow + ecol + c) = o;
;           }
.LBB0_480:
	s_or_b64 exec, exec, s[10:11]
	v_add_u32_e32 v0, 0xb0, v164
	v_cmp_gt_i32_e32 vcc, s36, v0
	s_movk_i32 s4, 0xff50
	s_nop 0
	v_cndmask_b32_e32 v10, v224, v225, vcc
	v_and_b32_e32 v11, v10, v0
	v_cmp_lt_i32_e32 vcc, s4, v163
	v_cmp_eq_u32_e64 s[6:7], 0, v11
	v_cmp_ne_u32_e64 s[4:5], 0, v11
	s_or_b64 s[6:7], vcc, s[6:7]
	s_and_saveexec_b64 s[10:11], s[6:7]
	s_cbranch_execz .LBB0_491
	s_movk_i32 s6, 0x4f
	v_cmp_gt_i32_e64 s[6:7], s6, v163
	v_cmp_eq_u32_e64 s[8:9], v11, v10
	v_cmp_ne_u32_e32 vcc, v11, v10
	s_or_b64 s[6:7], s[6:7], s[8:9]
	s_and_b64 exec, exec, s[6:7]
	s_cbranch_execz .LBB0_491
	v_add_u32_e32 v14, 0xfffffef8, v138
	v_mov_b32_e32 v10, 0
	v_mov_b32_e32 v12, 0
	v_mov_b32_e32 v13, 0
	s_and_saveexec_b64 s[6:7], s[4:5]
	v_lshl_add_u32 v11, v165, 1, v14
	ds_read_b64 v[12:13], v11
	s_or_b64 exec, exec, s[6:7]
	v_mov_b32_e32 v11, 0
	s_and_saveexec_b64 s[6:7], vcc
	v_lshl_add_u32 v10, v165, 1, v138
	ds_read_b64 v[10:11], v10 offset:264
	s_or_b64 exec, exec, s[6:7]
	s_waitcnt lgkmcnt(0)
	v_lshlrev_b32_e32 v18, 16, v12
	v_and_b32_e32 v19, 0xffff0000, v12
	s_waitcnt vmcnt(5)
	v_pk_mul_f32 v[18:19], v[50:51], v[18:19]
	v_lshlrev_b32_e32 v20, 16, v10
	v_pk_fma_f32 v[18:19], v[42:43], v[106:107], v[18:19]
	v_and_b32_e32 v21, 0xffff0000, v10
	v_pk_fma_f32 v[18:19], v[46:47], v[20:21], v[18:19]
	v_mov_b64_e32 v[16:17], s[2:3]
	s_waitcnt vmcnt(3)
	v_pk_add_f32 v[18:19], v[54:55], v[18:19]
	s_movk_i32 s2, 0x1600
	v_pk_mul_f32 v[20:21], v[18:19], v[18:19]
	v_mad_i64_i32 v[16:17], s[2:3], v0, s2, v[16:17]
	v_mov_b32_e32 v163, v162
	v_pk_mul_f32 v[6:7], v[6:7], v[162:163]
	v_lshlrev_b32_e32 v12, 16, v13
	v_and_b32_e32 v13, 0xffff0000, v13
	v_pk_mul_f32 v[8:9], v[8:9], v[162:163]
	v_pk_fma_f32 v[20:21], v[20:21], v[246:247], v[248:249]
	s_nop 0
	v_pk_mul_f32 v[20:21], v[20:21], v[18:19] neg_lo:[0,1] neg_hi:[0,1]
	s_nop 0
	v_exp_f32_e32 v20, v20
	v_exp_f32_e32 v21, v21
	s_nop 0
	v_pk_add_f32 v[20:21], v[20:21], v[250:251]
	s_nop 0
	v_rcp_f32_e32 v20, v20
	v_rcp_f32_e32 v21, v21
	s_nop 0
	s_nop 0
	v_pk_mul_f32 v[18:19], v[18:19], v[20:21]
	s_nop 0
	v_pk_mul_f32 v[6:7], v[6:7], v[18:19]
	s_nop 0
	v_cvt_pk_bf16_f32 v10, v6, v7
	v_pk_mul_f32 v[6:7], v[52:53], v[12:13]
	v_lshlrev_b32_e32 v12, 16, v11
	v_pk_fma_f32 v[6:7], v[44:45], v[104:105], v[6:7]
	v_and_b32_e32 v13, 0xffff0000, v11
	v_pk_fma_f32 v[6:7], v[48:49], v[12:13], v[6:7]
	s_nop 0
	v_pk_add_f32 v[6:7], v[56:57], v[6:7]
	s_nop 0
	v_pk_mul_f32 v[12:13], v[6:7], v[6:7]
	s_nop 0
	s_nop 0
	s_nop 0
	v_pk_fma_f32 v[12:13], v[12:13], v[246:247], v[248:249]
	s_nop 0
	v_pk_mul_f32 v[12:13], v[12:13], v[6:7] neg_lo:[0,1] neg_hi:[0,1]
	s_nop 0
	v_exp_f32_e32 v12, v12
	v_exp_f32_e32 v13, v13
	s_nop 0
	v_pk_add_f32 v[12:13], v[12:13], v[250:251]
	s_nop 0
	v_rcp_f32_e32 v12, v12
	v_rcp_f32_e32 v13, v13
	s_nop 0
	v_lshlrev_b32_e32 v0, 1, v165
	v_pk_mul_f32 v[6:7], v[6:7], v[12:13]
	s_nop 0
	v_pk_mul_f32 v[6:7], v[8:9], v[6:7]
	v_mov_b32_e32 v8, 0
	v_cvt_pk_bf16_f32 v11, v6, v7
	v_lshl_add_u64 v[6:7], v[16:17], 0, v[0:1]
	global_store_dwordx2 v[6:7], v[10:11], off
	v_or_b32_e32 v0, 16, v165
	v_mov_b32_e32 v10, 0
	v_mov_b32_e32 v11, 0
	s_and_saveexec_b64 s[2:3], s[4:5]
	v_lshl_add_u32 v9, v0, 1, v14
	ds_read_b64 v[10:11], v9
	s_or_b64 exec, exec, s[2:3]
	v_mov_b32_e32 v9, 0
	s_and_saveexec_b64 s[2:3], vcc
	v_lshl_add_u32 v0, v0, 1, v138
	ds_read_b64 v[8:9], v0 offset:264
	s_or_b64 exec, exec, s[2:3]
	s_waitcnt lgkmcnt(0)
	v_lshlrev_b32_e32 v12, 16, v10
	v_and_b32_e32 v13, 0xffff0000, v10
	v_pk_mul_f32 v[12:13], v[26:27], v[12:13]
	v_lshlrev_b32_e32 v14, 16, v8
	s_waitcnt vmcnt(2)
	v_pk_fma_f32 v[12:13], v[38:39], v[102:103], v[12:13]
	v_and_b32_e32 v15, 0xffff0000, v8
	s_waitcnt vmcnt(1)
	v_pk_fma_f32 v[12:13], v[34:35], v[14:15], v[12:13]
	v_lshlrev_b32_e32 v10, 16, v11
	v_pk_add_f32 v[12:13], v[30:31], v[12:13]
	v_and_b32_e32 v11, 0xffff0000, v11
	v_pk_mul_f32 v[14:15], v[12:13], v[12:13]
	v_pk_mul_f32 v[10:11], v[28:29], v[10:11]
	v_pk_fma_f32 v[10:11], v[40:41], v[98:99], v[10:11]
	v_lshlrev_b32_e32 v8, 16, v9
	v_and_b32_e32 v9, 0xffff0000, v9
	v_pk_fma_f32 v[8:9], v[36:37], v[8:9], v[10:11]
	v_pk_mul_f32 v[2:3], v[2:3], v[162:163]
	v_pk_add_f32 v[8:9], v[32:33], v[8:9]
	v_pk_mul_f32 v[10:11], v[8:9], v[8:9]
	v_pk_fma_f32 v[14:15], v[14:15], v[246:247], v[248:249]
	s_nop 0
	v_pk_mul_f32 v[14:15], v[14:15], v[12:13] neg_lo:[0,1] neg_hi:[0,1]
	s_nop 0
	v_exp_f32_e32 v14, v14
	v_exp_f32_e32 v15, v15
	s_nop 0
	v_pk_add_f32 v[14:15], v[14:15], v[250:251]
	s_nop 0
	v_rcp_f32_e32 v14, v14
	v_rcp_f32_e32 v15, v15
	s_nop 0
	v_pk_mul_f32 v[12:13], v[12:13], v[14:15]
	v_pk_mul_f32 v[4:5], v[4:5], v[162:163]
	v_pk_mul_f32 v[2:3], v[2:3], v[12:13]
	v_cvt_pk_bf16_f32 v2, v2, v3
	v_pk_fma_f32 v[10:11], v[10:11], v[246:247], v[248:249]
	s_nop 0
	v_pk_mul_f32 v[10:11], v[10:11], v[8:9] neg_lo:[0,1] neg_hi:[0,1]
	s_nop 0
	v_exp_f32_e32 v10, v10
	v_exp_f32_e32 v11, v11
	s_nop 0
	v_pk_add_f32 v[10:11], v[10:11], v[250:251]
	s_nop 0
	v_rcp_f32_e32 v10, v10
	v_rcp_f32_e32 v11, v11
	s_nop 0
	s_nop 0
	v_pk_mul_f32 v[8:9], v[8:9], v[10:11]
	s_nop 0
	v_pk_mul_f32 v[4:5], v[4:5], v[8:9]
	s_nop 0
	v_cvt_pk_bf16_f32 v3, v4, v5
	global_store_dwordx2 v[6:7], v[2:3], off offset:32
